# peeled first K-iteration of 4 GEMM loops (no accumulator zeroing) + attention exp/PV software-pipelined with spaced MFMAs
# speedup vs baseline: 1.0157x; 1.0157x over previous
; #define PG8_STAGE(bufoff, gbase, voff) do { _Pragma("unroll") for (int _i = 0; _i < 2; ++_i) \
;         __builtin_amdgcn_global_load_lds((const unsigned*)((const char*)(gbase) + (voff)[_i]), (PG8_LAS unsigned*)(lds + (bufoff) + ldsw + _i * 8192), 16, 0, 0); } while (0)
; #define PG8_LDA(dst, b, h) do { _Pragma("unroll") for (int m = 0; m < 4; ++m) _Pragma("unroll") for (int k = 0; k < 2; ++k) dst[m][k] = *(const PG8_LAS bf16x8*)(lds + PG8_SA(b, h) + aoff + m * 2048 + k * 1024); } while (0)
; #define PG8_LDB(dst, b, h) do { _Pragma("unroll") for (int n = 0; n < 2; ++n) _Pragma("unroll") for (int k = 0; k < 2; ++k) dst[n][k] = *(const PG8_LAS bf16x8*)(lds + PG8_SB(b, h) + boff + n * 2048 + k * 1024); } while (0)
; #define PG8_WAIT_V(n) asm volatile("s_waitcnt vmcnt(" #n ")" ::: "memory")
; #define PG8_WAIT_L(n) asm volatile("s_waitcnt lgkmcnt(" #n ")" ::: "memory")
; #define PG8_BAR __builtin_amdgcn_s_barrier()
; #define PG8_SCHED __builtin_amdgcn_sched_barrier(0)
; template <class Epi, class Sched, bool ALIGN_EPI = false, bool SP2 = false>
; __device__ __forceinline__ void gemm_phase(PG8_LAS unsigned char* lds, const Gemm g, const Sched& S, const Epi& E, const int wid_in) {
;     ...
;         const bool has_next = S.next(ui + 1, nxt);
;         const char* nA = has_next ? (const char*)g.A + (size_t)nxt.pm * tstep : cA; const char* nB = has_next ? (const char*)g.Bt + (size_t)nxt.pn * tstep : cB;
; #pragma unroll 1
;         for (int t = 0; t < nt; t += 2) {
;             const bool last = (t == nt - 2);
;             const char* a1 = cA + (size_t)(t + 1) * kstep;
;             const char* a2 = last ? nA : cA + (size_t)(t + 2) * kstep; const char* b2 = last ? nB : cB + (size_t)(t + 2) * kstep;
;             const char* a3 = a2 + kstep; const char* b3 = b2 + kstep;
;             if (last && has_next) S.a_ready(nxt);
;             if constexpr (SP2) {
;             PG8_LDB(B0, 0, 0); PG8_LDB(B1, 0, 1); PG8_SCHED; PG8_LDA(At, 0, 0); PG8_STAGE(PG8_SA(1, 1), a1 + hstep, voffA);
;             PG8_WAIT_V(8); PG8_WAIT_L(0); PG8_BAR; PG8_MMA(0, 0, At, B0); PG8_MMA(0, 1, At, B1); PG8_BAR; PG8_SCHED;
;             PG8_LDA(At, 0, 1); PG8_STAGE(PG8_SB(0, 0), b2, voffB); PG8_STAGE(PG8_SB(0, 1), b2 + hstep, voffB); PG8_STAGE(PG8_SA(0, 0), a2, voffA);
;             PG8_WAIT_V(8); PG8_WAIT_L(0); PG8_BAR; PG8_MMA(1, 0, At, B0); PG8_MMA(1, 1, At, B1); PG8_BAR; PG8_SCHED;
.LBB0_104:
	s_ashr_i32 s43, s42, 31
	s_lshl_b64 s[22:23], s[42:43], 19
	v_readlane_b32 s8, v243, 52
	v_readlane_b32 s9, v243, 53
	s_add_u32 s44, s8, s22
	s_addc_u32 s45, s9, s23
	s_and_b64 s[22:23], s[38:39], exec
	s_cselect_b32 s43, s45, s49
	s_cselect_b32 s57, s44, s48
	s_ashr_i32 s41, s40, 31
	s_lshl_b64 s[22:23], s[40:41], 19
	v_readlane_b32 s2, v243, 18
	s_add_u32 s46, s2, s22
	v_readlane_b32 s2, v243, 19
	s_addc_u32 s47, s2, s23
	s_and_b64 s[22:23], s[38:39], exec
	s_cselect_b32 s16, s47, s51
	s_cselect_b32 s41, s46, s50
	s_add_u32 s48, s48, 0x40080
	s_addc_u32 s49, s49, 0
	s_add_u32 s58, s50, 0x100
	s_addc_u32 s59, s51, 0
	s_mov_b32 s60, -2
	s_add_u32 s2, s48, 0xfffc0080
	s_addc_u32 s8, s49, -1
	s_add_i32 s22, 0, 0x10000
	s_cmp_eq_u32 s60, 12
	s_cselect_b32 s53, s43, s8
	s_cselect_b32 s52, s57, s2
	s_cselect_b32 s51, s16, s59
	s_cselect_b32 s50, s41, s58
	s_add_i32 s2, 0, 0x14000
	v_add_u32_e32 v154, s22, v144
	v_add_u32_e32 v170, s2, v144
	ds_read_b128 v[140:143], v154
	ds_read_b128 v[146:149], v154 offset:1024
	ds_read_b128 v[150:153], v154 offset:2048
	ds_read_b128 v[154:157], v154 offset:3072
	ds_read_b128 v[158:161], v170
	ds_read_b128 v[162:165], v170 offset:1024
	ds_read_b128 v[166:169], v170 offset:2048
	ds_read_b128 v[170:173], v170 offset:3072
	v_lshl_add_u64 v[228:229], s[48:49], 0, v[136:137]
	s_add_i32 m0, s4, 0xc000
	ds_read_b128 v[174:177], v145
	ds_read_b128 v[190:193], v145 offset:1024
	ds_read_b128 v[194:197], v145 offset:2048
	ds_read_b128 v[198:201], v145 offset:3072
	ds_read_b128 v[212:215], v145 offset:4096
	ds_read_b128 v[216:219], v145 offset:5120
	ds_read_b128 v[220:223], v145 offset:6144
	ds_read_b128 v[224:227], v145 offset:7168
	global_load_lds_dwordx4 v[228:229], off
	v_lshl_add_u64 v[228:229], s[48:49], 0, v[138:139]
	s_add_i32 m0, s4, 0xe000
	s_nop 0
	global_load_lds_dwordx4 v[228:229], off
	s_waitcnt vmcnt(8)
	s_waitcnt lgkmcnt(0)
	s_barrier
	s_setprio 1
	s_waitcnt lgkmcnt(0)
	v_mfma_f32_16x16x32_bf16 v[126:129], v[140:143], v[174:177], 0
	v_mfma_f32_16x16x32_bf16 v[122:125], v[150:153], v[174:177], 0
	v_mfma_f32_16x16x32_bf16 v[114:117], v[140:143], v[194:197], 0
	v_mfma_f32_16x16x32_bf16 v[110:113], v[150:153], v[194:197], 0
	v_mfma_f32_16x16x32_bf16 v[98:101], v[140:143], v[212:215], 0
	v_mfma_f32_16x16x32_bf16 v[94:97], v[150:153], v[212:215], 0
	v_mfma_f32_16x16x32_bf16 v[82:85], v[140:143], v[220:223], 0
	v_mfma_f32_16x16x32_bf16 v[78:81], v[150:153], v[220:223], 0
	v_mfma_f32_16x16x32_bf16 v[126:129], v[146:149], v[190:193], v[126:129]
	v_mfma_f32_16x16x32_bf16 v[122:125], v[154:157], v[190:193], v[122:125]
	v_mfma_f32_16x16x32_bf16 v[114:117], v[146:149], v[198:201], v[114:117]
	v_mfma_f32_16x16x32_bf16 v[110:113], v[154:157], v[198:201], v[110:113]
	v_mfma_f32_16x16x32_bf16 v[98:101], v[146:149], v[216:219], v[98:101]
	v_mfma_f32_16x16x32_bf16 v[94:97], v[154:157], v[216:219], v[94:97]
	v_mfma_f32_16x16x32_bf16 v[82:85], v[146:149], v[224:227], v[82:85]
	v_mfma_f32_16x16x32_bf16 v[78:81], v[154:157], v[224:227], v[78:81]
	s_setprio 0
	s_setprio 1
	v_mfma_f32_16x16x32_bf16 v[106:109], v[158:161], v[174:177], 0
	v_mfma_f32_16x16x32_bf16 v[118:121], v[166:169], v[174:177], 0
	v_mfma_f32_16x16x32_bf16 v[90:93], v[158:161], v[194:197], 0
	v_mfma_f32_16x16x32_bf16 v[102:105], v[166:169], v[194:197], 0
	v_mfma_f32_16x16x32_bf16 v[74:77], v[158:161], v[212:215], 0
	v_mfma_f32_16x16x32_bf16 v[86:89], v[166:169], v[212:215], 0
	v_mfma_f32_16x16x32_bf16 v[66:69], v[158:161], v[220:223], 0
	v_mfma_f32_16x16x32_bf16 v[70:73], v[166:169], v[220:223], 0
	v_mfma_f32_16x16x32_bf16 v[106:109], v[162:165], v[190:193], v[106:109]
	v_mfma_f32_16x16x32_bf16 v[118:121], v[170:173], v[190:193], v[118:121]
	v_mfma_f32_16x16x32_bf16 v[90:93], v[162:165], v[198:201], v[90:93]
	v_mfma_f32_16x16x32_bf16 v[102:105], v[170:173], v[198:201], v[102:105]
	v_mfma_f32_16x16x32_bf16 v[74:77], v[162:165], v[216:219], v[74:77]
	v_mfma_f32_16x16x32_bf16 v[86:89], v[170:173], v[216:219], v[86:89]
	v_mfma_f32_16x16x32_bf16 v[66:69], v[162:165], v[224:227], v[66:69]
	v_mfma_f32_16x16x32_bf16 v[70:73], v[170:173], v[224:227], v[70:73]
	s_setprio 0
	s_barrier
	s_add_i32 s8, s22, s3
	v_lshl_add_u64 v[228:229], s[50:51], 0, v[0:1]
	s_mov_b32 m0, s8
	ds_read_b128 v[174:177], v145 offset:16384
	ds_read_b128 v[190:193], v145 offset:17408
	ds_read_b128 v[194:197], v145 offset:18432
	ds_read_b128 v[198:201], v145 offset:19456
	ds_read_b128 v[212:215], v145 offset:20480
	ds_read_b128 v[216:219], v145 offset:21504
	ds_read_b128 v[220:223], v145 offset:22528
	ds_read_b128 v[224:227], v145 offset:23552
	global_load_lds_dwordx4 v[228:229], off
	s_add_i32 m0, s8, 0x2000
	s_add_u32 s22, s50, 0x40000
	v_lshl_add_u64 v[230:231], s[50:51], 0, v[130:131]
	s_addc_u32 s23, s51, 0
	s_add_i32 s2, s2, s3
	global_load_lds_dwordx4 v[230:231], off
	v_lshl_add_u64 v[232:233], s[22:23], 0, v[0:1]
	s_mov_b32 m0, s2
	v_lshl_add_u64 v[234:235], s[52:53], 0, v[132:133]
	global_load_lds_dwordx4 v[232:233], off
	v_lshl_add_u64 v[232:233], s[22:23], 0, v[130:131]
	s_add_i32 m0, s2, 0x2000
	s_nop 0
	global_load_lds_dwordx4 v[232:233], off
	v_lshl_add_u64 v[232:233], s[52:53], 0, v[134:135]
	s_mov_b32 m0, s4
	s_nop 0
	global_load_lds_dwordx4 v[232:233], off
	s_mov_b32 m0, s5
	s_nop 0
	global_load_lds_dwordx4 v[234:235], off
	s_waitcnt vmcnt(8)
	s_waitcnt lgkmcnt(0)
	s_barrier
; #define PG8_STAGE(bufoff, gbase, voff) do { _Pragma("unroll") for (int _i = 0; _i < 2; ++_i) \
;         __builtin_amdgcn_global_load_lds((const unsigned*)((const char*)(gbase) + (voff)[_i]), (PG8_LAS unsigned*)(lds + (bufoff) + ldsw + _i * 8192), 16, 0, 0); } while (0)
; #define PG8_LDA(dst, b, h) do { _Pragma("unroll") for (int m = 0; m < 4; ++m) _Pragma("unroll") for (int k = 0; k < 2; ++k) dst[m][k] = *(const PG8_LAS bf16x8*)(lds + PG8_SA(b, h) + aoff + m * 2048 + k * 1024); } while (0)
; #define PG8_LDB(dst, b, h) do { _Pragma("unroll") for (int n = 0; n < 2; ++n) _Pragma("unroll") for (int k = 0; k < 2; ++k) dst[n][k] = *(const PG8_LAS bf16x8*)(lds + PG8_SB(b, h) + boff + n * 2048 + k * 1024); } while (0)
; #define PG8_MMA(ai, bj, At, Bt) do { __builtin_amdgcn_s_setprio(1); _Pragma("unroll") for (int m = 0; m < 4; ++m) _Pragma("unroll") for (int n = 0; n < 2; ++n) _Pragma("unroll") for (int k = 0; k < 2; ++k) \
;         acc[ai][bj][m][n] = __builtin_amdgcn_mfma_f32_16x16x32_bf16(Bt[n][k], At[m][k], acc[ai][bj][m][n], 0, 0, 0); __builtin_amdgcn_s_setprio(0); } while (0)
; #define PG8_WAIT_V(n) asm volatile("s_waitcnt vmcnt(" #n ")" ::: "memory")
; #define PG8_WAIT_L(n) asm volatile("s_waitcnt lgkmcnt(" #n ")" ::: "memory")
; #define PG8_BAR __builtin_amdgcn_s_barrier()
; #define PG8_SCHED __builtin_amdgcn_sched_barrier(0)
; template <class Epi, class Sched, bool ALIGN_EPI = false, bool SP2 = false>
; __device__ __forceinline__ void gemm_phase(PG8_LAS unsigned char* lds, const Gemm g, const Sched& S, const Epi& E, const int wid_in) {
;     ...
;             PG8_WAIT_V(8); PG8_WAIT_L(0); PG8_BAR; PG8_MMA(1, 0, At, B0); PG8_MMA(1, 1, At, B1); PG8_BAR; PG8_SCHED;
;             PG8_LDB(B0, 1, 0); PG8_LDB(B1, 1, 1); PG8_SCHED; PG8_LDA(At, 1, 0); PG8_STAGE(PG8_SA(0, 1), a2 + hstep, voffA);
;             PG8_WAIT_V(8); PG8_WAIT_L(0); PG8_BAR; PG8_MMA(0, 0, At, B0); PG8_MMA(0, 1, At, B1); PG8_BAR; PG8_SCHED;
	s_setprio 1
	s_waitcnt lgkmcnt(0)
	v_mfma_f32_16x16x32_bf16 v[62:65], v[140:143], v[174:177], 0
	v_mfma_f32_16x16x32_bf16 v[58:61], v[150:153], v[174:177], 0
	v_mfma_f32_16x16x32_bf16 v[50:53], v[140:143], v[194:197], 0
	v_mfma_f32_16x16x32_bf16 v[46:49], v[150:153], v[194:197], 0
	v_mfma_f32_16x16x32_bf16 v[34:37], v[140:143], v[212:215], 0
	v_mfma_f32_16x16x32_bf16 v[30:33], v[150:153], v[212:215], 0
	v_mfma_f32_16x16x32_bf16 v[18:21], v[140:143], v[220:223], 0
	v_mfma_f32_16x16x32_bf16 v[14:17], v[150:153], v[220:223], 0
	v_mfma_f32_16x16x32_bf16 v[62:65], v[146:149], v[190:193], v[62:65]
	v_mfma_f32_16x16x32_bf16 v[58:61], v[154:157], v[190:193], v[58:61]
	v_mfma_f32_16x16x32_bf16 v[50:53], v[146:149], v[198:201], v[50:53]
	v_mfma_f32_16x16x32_bf16 v[46:49], v[154:157], v[198:201], v[46:49]
	v_mfma_f32_16x16x32_bf16 v[34:37], v[146:149], v[216:219], v[34:37]
	v_mfma_f32_16x16x32_bf16 v[30:33], v[154:157], v[216:219], v[30:33]
	v_mfma_f32_16x16x32_bf16 v[18:21], v[146:149], v[224:227], v[18:21]
	v_mfma_f32_16x16x32_bf16 v[14:17], v[154:157], v[224:227], v[14:17]
	s_setprio 0
	s_setprio 1
	v_mfma_f32_16x16x32_bf16 v[42:45], v[158:161], v[174:177], 0
	v_mfma_f32_16x16x32_bf16 v[54:57], v[166:169], v[174:177], 0
	v_mfma_f32_16x16x32_bf16 v[26:29], v[158:161], v[194:197], 0
	v_mfma_f32_16x16x32_bf16 v[38:41], v[166:169], v[194:197], 0
	v_mfma_f32_16x16x32_bf16 v[10:13], v[158:161], v[212:215], 0
	v_mfma_f32_16x16x32_bf16 v[22:25], v[166:169], v[212:215], 0
	v_mfma_f32_16x16x32_bf16 v[2:5], v[158:161], v[220:223], 0
	v_mfma_f32_16x16x32_bf16 v[6:9], v[166:169], v[220:223], 0
	v_mfma_f32_16x16x32_bf16 v[42:45], v[162:165], v[190:193], v[42:45]
	v_mfma_f32_16x16x32_bf16 v[54:57], v[170:173], v[190:193], v[54:57]
	v_mfma_f32_16x16x32_bf16 v[26:29], v[162:165], v[198:201], v[26:29]
	v_mfma_f32_16x16x32_bf16 v[38:41], v[170:173], v[198:201], v[38:41]
	v_mfma_f32_16x16x32_bf16 v[10:13], v[162:165], v[216:219], v[10:13]
	v_mfma_f32_16x16x32_bf16 v[22:25], v[170:173], v[216:219], v[22:25]
	v_mfma_f32_16x16x32_bf16 v[2:5], v[162:165], v[224:227], v[2:5]
	v_mfma_f32_16x16x32_bf16 v[6:9], v[170:173], v[224:227], v[6:9]
	s_setprio 0
	s_barrier
	s_add_i32 s2, 0, 0x18000
	s_add_i32 s8, 0, 0x1c000
	v_add_u32_e32 v154, s2, v144
	v_add_u32_e32 v170, s8, v144
	ds_read_b128 v[140:143], v154
	ds_read_b128 v[146:149], v154 offset:1024
	ds_read_b128 v[150:153], v154 offset:2048
	ds_read_b128 v[154:157], v154 offset:3072
	ds_read_b128 v[158:161], v170
	ds_read_b128 v[162:165], v170 offset:1024
	ds_read_b128 v[166:169], v170 offset:2048
	ds_read_b128 v[170:173], v170 offset:3072
	s_add_u32 s22, s52, 0x40000
	s_addc_u32 s23, s53, 0
	s_mov_b32 m0, s12
	v_lshl_add_u64 v[236:237], s[22:23], 0, v[134:135]
	ds_read_b128 v[174:177], v145 offset:32768
	ds_read_b128 v[190:193], v145 offset:33792
	ds_read_b128 v[194:197], v145 offset:34816
	ds_read_b128 v[198:201], v145 offset:35840
	ds_read_b128 v[212:215], v145 offset:36864
	ds_read_b128 v[216:219], v145 offset:37888
	ds_read_b128 v[220:223], v145 offset:38912
	ds_read_b128 v[224:227], v145 offset:39936
	global_load_lds_dwordx4 v[236:237], off
	v_lshl_add_u64 v[236:237], s[22:23], 0, v[132:133]
	s_mov_b32 m0, s13
	s_nop 0
	global_load_lds_dwordx4 v[236:237], off
	s_waitcnt vmcnt(8)
	s_waitcnt lgkmcnt(0)
	s_barrier
	s_setprio 1
	s_waitcnt lgkmcnt(0)
	v_mfma_f32_16x16x32_bf16 v[126:129], v[140:143], v[174:177], v[126:129]
	v_mfma_f32_16x16x32_bf16 v[122:125], v[150:153], v[174:177], v[122:125]
	v_mfma_f32_16x16x32_bf16 v[114:117], v[140:143], v[194:197], v[114:117]
	v_mfma_f32_16x16x32_bf16 v[110:113], v[150:153], v[194:197], v[110:113]
	v_mfma_f32_16x16x32_bf16 v[98:101], v[140:143], v[212:215], v[98:101]
	v_mfma_f32_16x16x32_bf16 v[94:97], v[150:153], v[212:215], v[94:97]
	v_mfma_f32_16x16x32_bf16 v[82:85], v[140:143], v[220:223], v[82:85]
	v_mfma_f32_16x16x32_bf16 v[78:81], v[150:153], v[220:223], v[78:81]
	v_mfma_f32_16x16x32_bf16 v[126:129], v[146:149], v[190:193], v[126:129]
	v_mfma_f32_16x16x32_bf16 v[122:125], v[154:157], v[190:193], v[122:125]
	v_mfma_f32_16x16x32_bf16 v[114:117], v[146:149], v[198:201], v[114:117]
	v_mfma_f32_16x16x32_bf16 v[110:113], v[154:157], v[198:201], v[110:113]
	v_mfma_f32_16x16x32_bf16 v[98:101], v[146:149], v[216:219], v[98:101]
	v_mfma_f32_16x16x32_bf16 v[94:97], v[154:157], v[216:219], v[94:97]
	v_mfma_f32_16x16x32_bf16 v[82:85], v[146:149], v[224:227], v[82:85]
	v_mfma_f32_16x16x32_bf16 v[78:81], v[154:157], v[224:227], v[78:81]
	s_setprio 0
	s_setprio 1
	v_mfma_f32_16x16x32_bf16 v[106:109], v[158:161], v[174:177], v[106:109]
	v_mfma_f32_16x16x32_bf16 v[118:121], v[166:169], v[174:177], v[118:121]
	v_mfma_f32_16x16x32_bf16 v[90:93], v[158:161], v[194:197], v[90:93]
	v_mfma_f32_16x16x32_bf16 v[102:105], v[166:169], v[194:197], v[102:105]
	v_mfma_f32_16x16x32_bf16 v[74:77], v[158:161], v[212:215], v[74:77]
	v_mfma_f32_16x16x32_bf16 v[86:89], v[166:169], v[212:215], v[86:89]
	v_mfma_f32_16x16x32_bf16 v[66:69], v[158:161], v[220:223], v[66:69]
	v_mfma_f32_16x16x32_bf16 v[70:73], v[166:169], v[220:223], v[70:73]
	v_mfma_f32_16x16x32_bf16 v[106:109], v[162:165], v[190:193], v[106:109]
	v_mfma_f32_16x16x32_bf16 v[118:121], v[170:173], v[190:193], v[118:121]
	v_mfma_f32_16x16x32_bf16 v[90:93], v[162:165], v[198:201], v[90:93]
	v_mfma_f32_16x16x32_bf16 v[102:105], v[170:173], v[198:201], v[102:105]
	v_mfma_f32_16x16x32_bf16 v[74:77], v[162:165], v[216:219], v[74:77]
	v_mfma_f32_16x16x32_bf16 v[86:89], v[170:173], v[216:219], v[86:89]
	v_mfma_f32_16x16x32_bf16 v[66:69], v[162:165], v[224:227], v[66:69]
	v_mfma_f32_16x16x32_bf16 v[70:73], v[170:173], v[224:227], v[70:73]
	s_setprio 0
	s_barrier
; #define PG8_STAGE(bufoff, gbase, voff) do { _Pragma("unroll") for (int _i = 0; _i < 2; ++_i) \
;         __builtin_amdgcn_global_load_lds((const unsigned*)((const char*)(gbase) + (voff)[_i]), (PG8_LAS unsigned*)(lds + (bufoff) + ldsw + _i * 8192), 16, 0, 0); } while (0)
; #define PG8_LDA(dst, b, h) do { _Pragma("unroll") for (int m = 0; m < 4; ++m) _Pragma("unroll") for (int k = 0; k < 2; ++k) dst[m][k] = *(const PG8_LAS bf16x8*)(lds + PG8_SA(b, h) + aoff + m * 2048 + k * 1024); } while (0)
; #define PG8_MMA(ai, bj, At, Bt) do { __builtin_amdgcn_s_setprio(1); _Pragma("unroll") for (int m = 0; m < 4; ++m) _Pragma("unroll") for (int n = 0; n < 2; ++n) _Pragma("unroll") for (int k = 0; k < 2; ++k) \
;         acc[ai][bj][m][n] = __builtin_amdgcn_mfma_f32_16x16x32_bf16(Bt[n][k], At[m][k], acc[ai][bj][m][n], 0, 0, 0); __builtin_amdgcn_s_setprio(0); } while (0)
; #define PG8_WAIT_V(n) asm volatile("s_waitcnt vmcnt(" #n ")" ::: "memory")
; #define PG8_WAIT_L(n) asm volatile("s_waitcnt lgkmcnt(" #n ")" ::: "memory")
; #define PG8_BAR __builtin_amdgcn_s_barrier()
; #define PG8_SCHED __builtin_amdgcn_sched_barrier(0)
; template <class Epi, class Sched, bool ALIGN_EPI = false, bool SP2 = false>
; __device__ __forceinline__ void gemm_phase(PG8_LAS unsigned char* lds, const Gemm g, const Sched& S, const Epi& E, const int wid_in) {
;     ...
;         for (int t = 0; t < nt; t += 2) {
;     ...
;             PG8_LDA(At, 1, 1); PG8_STAGE(PG8_SB(1, 0), b3, voffB); PG8_STAGE(PG8_SB(1, 1), b3 + hstep, voffB); PG8_STAGE(PG8_SA(1, 0), a3, voffA);
;             PG8_WAIT_V(8); PG8_WAIT_L(0); PG8_BAR; PG8_MMA(1, 0, At, B0); PG8_MMA(1, 1, At, B1); PG8_BAR; PG8_SCHED;
	s_add_i32 s2, s2, s3
	v_lshl_add_u64 v[228:229], v[228:229], 0, s[64:65]
	s_mov_b32 m0, s2
	ds_read_b128 v[174:177], v145 offset:49152
	ds_read_b128 v[190:193], v145 offset:50176
	ds_read_b128 v[194:197], v145 offset:51200
	ds_read_b128 v[198:201], v145 offset:52224
	ds_read_b128 v[212:215], v145 offset:53248
	ds_read_b128 v[216:219], v145 offset:54272
	ds_read_b128 v[220:223], v145 offset:55296
	ds_read_b128 v[224:227], v145 offset:56320
	global_load_lds_dwordx4 v[228:229], off
	s_add_i32 m0, s2, 0x2000
	s_add_u32 s22, s50, 0x40080
	v_lshl_add_u64 v[228:229], v[230:231], 0, s[64:65]
	s_addc_u32 s23, s51, 0
	s_add_i32 s2, s8, s3
	global_load_lds_dwordx4 v[228:229], off
	v_lshl_add_u64 v[228:229], s[22:23], 0, v[0:1]
	s_mov_b32 m0, s2
	s_nop 0
	global_load_lds_dwordx4 v[228:229], off
	v_lshl_add_u64 v[228:229], s[22:23], 0, v[130:131]
	s_add_i32 m0, s2, 0x2000
	s_nop 0
	global_load_lds_dwordx4 v[228:229], off
	v_lshl_add_u64 v[228:229], v[232:233], 0, s[64:65]
	s_mov_b32 m0, s36
	s_nop 0
	global_load_lds_dwordx4 v[228:229], off
	v_lshl_add_u64 v[228:229], v[234:235], 0, s[64:65]
	s_mov_b32 m0, s37
	s_nop 0
	global_load_lds_dwordx4 v[228:229], off
	s_waitcnt vmcnt(8)
	s_waitcnt lgkmcnt(0)
	s_barrier
	s_setprio 1
	s_waitcnt lgkmcnt(0)
	v_mfma_f32_16x16x32_bf16 v[62:65], v[140:143], v[174:177], v[62:65]
	v_mfma_f32_16x16x32_bf16 v[58:61], v[150:153], v[174:177], v[58:61]
	v_mfma_f32_16x16x32_bf16 v[50:53], v[140:143], v[194:197], v[50:53]
	v_mfma_f32_16x16x32_bf16 v[46:49], v[150:153], v[194:197], v[46:49]
	v_mfma_f32_16x16x32_bf16 v[34:37], v[140:143], v[212:215], v[34:37]
	v_mfma_f32_16x16x32_bf16 v[30:33], v[150:153], v[212:215], v[30:33]
	v_mfma_f32_16x16x32_bf16 v[18:21], v[140:143], v[220:223], v[18:21]
	v_mfma_f32_16x16x32_bf16 v[14:17], v[150:153], v[220:223], v[14:17]
	v_mfma_f32_16x16x32_bf16 v[62:65], v[146:149], v[190:193], v[62:65]
	v_mfma_f32_16x16x32_bf16 v[58:61], v[154:157], v[190:193], v[58:61]
	v_mfma_f32_16x16x32_bf16 v[50:53], v[146:149], v[198:201], v[50:53]
	v_mfma_f32_16x16x32_bf16 v[46:49], v[154:157], v[198:201], v[46:49]
	v_mfma_f32_16x16x32_bf16 v[34:37], v[146:149], v[216:219], v[34:37]
	v_mfma_f32_16x16x32_bf16 v[30:33], v[154:157], v[216:219], v[30:33]
	v_mfma_f32_16x16x32_bf16 v[18:21], v[146:149], v[224:227], v[18:21]
	v_mfma_f32_16x16x32_bf16 v[14:17], v[154:157], v[224:227], v[14:17]
	s_setprio 0
	s_setprio 1
	v_mfma_f32_16x16x32_bf16 v[42:45], v[158:161], v[174:177], v[42:45]
	v_mfma_f32_16x16x32_bf16 v[54:57], v[166:169], v[174:177], v[54:57]
	v_mfma_f32_16x16x32_bf16 v[26:29], v[158:161], v[194:197], v[26:29]
	v_mfma_f32_16x16x32_bf16 v[38:41], v[166:169], v[194:197], v[38:41]
	v_mfma_f32_16x16x32_bf16 v[10:13], v[158:161], v[212:215], v[10:13]
	v_mfma_f32_16x16x32_bf16 v[22:25], v[166:169], v[212:215], v[22:25]
	v_mfma_f32_16x16x32_bf16 v[2:5], v[158:161], v[220:223], v[2:5]
	v_mfma_f32_16x16x32_bf16 v[6:9], v[166:169], v[220:223], v[6:9]
	v_mfma_f32_16x16x32_bf16 v[42:45], v[162:165], v[190:193], v[42:45]
	v_mfma_f32_16x16x32_bf16 v[54:57], v[170:173], v[190:193], v[54:57]
	v_mfma_f32_16x16x32_bf16 v[26:29], v[162:165], v[198:201], v[26:29]
	v_mfma_f32_16x16x32_bf16 v[38:41], v[170:173], v[198:201], v[38:41]
	v_mfma_f32_16x16x32_bf16 v[10:13], v[162:165], v[216:219], v[10:13]
	v_mfma_f32_16x16x32_bf16 v[22:25], v[170:173], v[216:219], v[22:25]
	v_mfma_f32_16x16x32_bf16 v[2:5], v[162:165], v[224:227], v[2:5]
	v_mfma_f32_16x16x32_bf16 v[6:9], v[170:173], v[224:227], v[6:9]
	s_setprio 0
	s_barrier
	s_add_i32 s60, s60, 2
	s_add_u32 s48, s48, 0x100
	s_addc_u32 s49, s49, 0
	s_add_u32 s58, s58, 0x100
	s_addc_u32 s59, s59, 0
	s_cmp_gt_u32 s60, 13

; DI unsigned pk2s(float lo, float hi) { f32x2_t v = {lo, hi}; bf16x2_t q = __builtin_convertvector(v, bf16x2_t); return __builtin_bit_cast(unsigned, q); }
; #define MFMA32(a, b, c) __builtin_amdgcn_mfma_f32_32x32x16_bf16((a), (b), (c), 0, 0, 0)
; DI void attn_unit(const bf16_t* Qb, const bf16_t* Kb, const bf16_t* Vt, bf16_t* MIX, int b, int h, int qb, char* lds, int tid_in) {
;     ...
;             float rs = 0.f;
; #pragma unroll
;             for (int kb = 0; kb < 4; ++kb)
; #pragma unroll
;                 for (int i = 0; i < 16; ++i) { const float e = __builtin_amdgcn_exp2f(p[kb][i]); p[kb][i] = e; rs += e; }
;             l_run += rs;
;             {
;                 bf16x8 vf[2][2];
;                 vf[0][0] = *(const bf16x8*)(vb_ + r * AV_PITCH + (8 * hh) * 2); vf[0][1] = *(const bf16x8*)(vb_ + (32 + r) * AV_PITCH + (8 * hh) * 2);
; #pragma unroll
;                 for (int G = 0; G < 8; ++G) { const int kb = G >> 1, s2 = G & 1;
;                     if (G + 1 < 8) { vf[(G + 1) & 1][0] = *(const bf16x8*)(vb_ + r * AV_PITCH + (16 * (G + 1) + 8 * hh) * 2); vf[(G + 1) & 1][1] = *(const bf16x8*)(vb_ + (32 + r) * AV_PITCH + (16 * (G + 1) + 8 * hh) * 2); }
;                     u32x4 pw; pw.x = pk2s(p[kb][8 * s2], p[kb][8 * s2 + 1]); pw.y = pk2s(p[kb][8 * s2 + 2], p[kb][8 * s2 + 3]); pw.z = pk2s(p[kb][8 * s2 + 4], p[kb][8 * s2 + 5]); pw.w = pk2s(p[kb][8 * s2 + 6], p[kb][8 * s2 + 7]);
;                     const bf16x8 pa = __builtin_bit_cast(bf16x8, pw);
;                     __builtin_amdgcn_sched_barrier(0);
;                     __builtin_amdgcn_s_setprio(1);
;                     o0 = MFMA32(pa, vf[G & 1][0], o0); o1 = MFMA32(pa, vf[G & 1][1], o1);
;                     __builtin_amdgcn_s_setprio(0);
;                     __builtin_amdgcn_sched_barrier(0);
;                 }
.LBB0_467:
	v_add3_u32 v244, s16, v175, v176
	ds_read_b128 v[190:193], v244 offset:24576
	ds_read_b128 v[194:197], v244 offset:33280
	ds_read_b128 v[198:201], v244 offset:24608
	ds_read_b128 v[212:215], v244 offset:33312
	v_exp_f32_e32 v82, v82
	v_exp_f32_e32 v83, v83
	v_mov_b32_e32 v245, v82
	v_exp_f32_e32 v84, v84
	v_mov_b32_e32 v246, v83
	v_exp_f32_e32 v85, v85
	v_add_f32_e32 v245, v84, v245
	v_exp_f32_e32 v86, v86
	v_add_f32_e32 v246, v85, v246
	v_exp_f32_e32 v87, v87
	v_add_f32_e32 v245, v86, v245
	v_exp_f32_e32 v88, v88
	v_add_f32_e32 v246, v87, v246
	v_exp_f32_e32 v89, v89
	v_add_f32_e32 v245, v88, v245
	v_exp_f32_e32 v90, v90
	v_add_f32_e32 v246, v89, v246
	v_exp_f32_e32 v91, v91
	v_add_f32_e32 v245, v90, v245
	v_exp_f32_e32 v92, v92
	v_add_f32_e32 v246, v91, v246
	v_exp_f32_e32 v93, v93
	v_add_f32_e32 v245, v92, v245
	v_exp_f32_e32 v94, v94
	v_add_f32_e32 v246, v93, v246
	v_exp_f32_e32 v95, v95
	v_add_f32_e32 v245, v94, v245
	v_exp_f32_e32 v96, v96
	v_add_f32_e32 v246, v95, v246
	v_exp_f32_e32 v97, v97
	v_add_f32_e32 v245, v96, v245
	v_cvt_pk_bf16_f32 v216, v82, v83
	v_cvt_pk_bf16_f32 v217, v84, v85
	v_cvt_pk_bf16_f32 v218, v86, v87
	v_cvt_pk_bf16_f32 v219, v88, v89
	s_waitcnt lgkmcnt(2)
	s_nop 0
	v_mfma_f32_32x32x16_bf16 v[18:33], v[216:219], v[190:193], v[18:33]
	v_exp_f32_e32 v66, v66
	v_add_f32_e32 v246, v97, v246
	v_exp_f32_e32 v67, v67
	v_add_f32_e32 v245, v66, v245
	v_exp_f32_e32 v68, v68
	v_add_f32_e32 v246, v67, v246
	v_exp_f32_e32 v69, v69
	v_add_f32_e32 v245, v68, v245
	v_mfma_f32_32x32x16_bf16 v[2:17], v[216:219], v[194:197], v[2:17]
	ds_read_b128 v[190:193], v244 offset:24640
	ds_read_b128 v[194:197], v244 offset:33344
	v_exp_f32_e32 v70, v70
	v_add_f32_e32 v246, v69, v246
	v_exp_f32_e32 v71, v71
	v_add_f32_e32 v245, v70, v245
	v_exp_f32_e32 v72, v72
	v_add_f32_e32 v246, v71, v246
	v_exp_f32_e32 v73, v73
	v_add_f32_e32 v245, v72, v245
	v_cvt_pk_bf16_f32 v224, v90, v91
	v_cvt_pk_bf16_f32 v225, v92, v93
	v_cvt_pk_bf16_f32 v226, v94, v95
	v_cvt_pk_bf16_f32 v227, v96, v97
	s_waitcnt lgkmcnt(2)
	s_nop 0
	v_mfma_f32_32x32x16_bf16 v[18:33], v[224:227], v[198:201], v[18:33]
	v_exp_f32_e32 v74, v74
	v_add_f32_e32 v246, v73, v246
	v_exp_f32_e32 v75, v75
	v_add_f32_e32 v245, v74, v245
	v_exp_f32_e32 v76, v76
	v_add_f32_e32 v246, v75, v246
	v_exp_f32_e32 v77, v77
	v_add_f32_e32 v245, v76, v245
	v_mfma_f32_32x32x16_bf16 v[2:17], v[224:227], v[212:215], v[2:17]
	ds_read_b128 v[198:201], v244 offset:24672
	ds_read_b128 v[212:215], v244 offset:33376
	v_exp_f32_e32 v78, v78
	v_add_f32_e32 v246, v77, v246
	v_exp_f32_e32 v79, v79
	v_add_f32_e32 v245, v78, v245
	v_exp_f32_e32 v80, v80
	v_add_f32_e32 v246, v79, v246
	v_exp_f32_e32 v81, v81
	v_add_f32_e32 v245, v80, v245
	v_cvt_pk_bf16_f32 v216, v66, v67
	v_cvt_pk_bf16_f32 v217, v68, v69
	v_cvt_pk_bf16_f32 v218, v70, v71
	v_cvt_pk_bf16_f32 v219, v72, v73
	s_waitcnt lgkmcnt(2)
	s_nop 0
	v_mfma_f32_32x32x16_bf16 v[18:33], v[216:219], v[190:193], v[18:33]
	v_exp_f32_e32 v50, v50
	v_add_f32_e32 v246, v81, v246
	v_exp_f32_e32 v51, v51
	v_add_f32_e32 v245, v50, v245
	v_exp_f32_e32 v52, v52
	v_add_f32_e32 v246, v51, v246
	v_exp_f32_e32 v53, v53
	v_add_f32_e32 v245, v52, v245
	v_mfma_f32_32x32x16_bf16 v[2:17], v[216:219], v[194:197], v[2:17]
	ds_read_b128 v[190:193], v244 offset:24704
	ds_read_b128 v[194:197], v244 offset:33408
	v_exp_f32_e32 v54, v54
	v_add_f32_e32 v246, v53, v246
	v_exp_f32_e32 v55, v55
	v_add_f32_e32 v245, v54, v245
	v_exp_f32_e32 v56, v56
	v_add_f32_e32 v246, v55, v246
	v_exp_f32_e32 v57, v57
	v_add_f32_e32 v245, v56, v245
	v_cvt_pk_bf16_f32 v224, v74, v75
	v_cvt_pk_bf16_f32 v225, v76, v77
	v_cvt_pk_bf16_f32 v226, v78, v79
	v_cvt_pk_bf16_f32 v227, v80, v81
	s_waitcnt lgkmcnt(2)
	s_nop 0
	v_mfma_f32_32x32x16_bf16 v[18:33], v[224:227], v[198:201], v[18:33]
	v_exp_f32_e32 v58, v58
	v_add_f32_e32 v246, v57, v246
	v_exp_f32_e32 v59, v59
	v_add_f32_e32 v245, v58, v245
	v_exp_f32_e32 v60, v60
	v_add_f32_e32 v246, v59, v246
	v_exp_f32_e32 v61, v61
	v_add_f32_e32 v245, v60, v245
	v_mfma_f32_32x32x16_bf16 v[2:17], v[224:227], v[212:215], v[2:17]
	ds_read_b128 v[198:201], v244 offset:24736
	ds_read_b128 v[212:215], v244 offset:33440
	v_exp_f32_e32 v62, v62
	v_add_f32_e32 v246, v61, v246
	v_exp_f32_e32 v63, v63
	v_add_f32_e32 v245, v62, v245
	v_exp_f32_e32 v64, v64
	v_add_f32_e32 v246, v63, v246
	v_exp_f32_e32 v65, v65
	v_add_f32_e32 v245, v64, v245
	v_cvt_pk_bf16_f32 v216, v50, v51
	v_cvt_pk_bf16_f32 v217, v52, v53
	v_cvt_pk_bf16_f32 v218, v54, v55
	v_cvt_pk_bf16_f32 v219, v56, v57
	s_waitcnt lgkmcnt(2)
	s_nop 0
	v_mfma_f32_32x32x16_bf16 v[18:33], v[216:219], v[190:193], v[18:33]
	v_exp_f32_e32 v34, v34
	v_add_f32_e32 v246, v65, v246
	v_exp_f32_e32 v35, v35
	v_add_f32_e32 v245, v34, v245
	v_exp_f32_e32 v36, v36
	v_add_f32_e32 v246, v35, v246
	v_exp_f32_e32 v37, v37
	v_add_f32_e32 v245, v36, v245
	v_mfma_f32_32x32x16_bf16 v[2:17], v[216:219], v[194:197], v[2:17]
	ds_read_b128 v[190:193], v244 offset:24768
	ds_read_b128 v[194:197], v244 offset:33472
	v_exp_f32_e32 v38, v38
	v_add_f32_e32 v246, v37, v246
	v_exp_f32_e32 v39, v39
	v_add_f32_e32 v245, v38, v245
	v_exp_f32_e32 v40, v40
	v_add_f32_e32 v246, v39, v246
	v_exp_f32_e32 v41, v41
	v_add_f32_e32 v245, v40, v245
	v_cvt_pk_bf16_f32 v224, v58, v59
	v_cvt_pk_bf16_f32 v225, v60, v61
	v_cvt_pk_bf16_f32 v226, v62, v63
	v_cvt_pk_bf16_f32 v227, v64, v65
	s_waitcnt lgkmcnt(2)
	s_nop 0
	v_mfma_f32_32x32x16_bf16 v[18:33], v[224:227], v[198:201], v[18:33]
	v_exp_f32_e32 v42, v42
	v_add_f32_e32 v246, v41, v246
	v_exp_f32_e32 v43, v43
	v_add_f32_e32 v245, v42, v245
	v_exp_f32_e32 v44, v44
	v_add_f32_e32 v246, v43, v246
	v_exp_f32_e32 v45, v45
	v_add_f32_e32 v245, v44, v245
	v_mfma_f32_32x32x16_bf16 v[2:17], v[224:227], v[212:215], v[2:17]
	ds_read_b128 v[198:201], v244 offset:24800
	ds_read_b128 v[212:215], v244 offset:33504
	v_exp_f32_e32 v46, v46
	v_add_f32_e32 v246, v45, v246
	v_exp_f32_e32 v47, v47
	v_add_f32_e32 v245, v46, v245
	v_exp_f32_e32 v48, v48
	v_add_f32_e32 v246, v47, v246
	v_exp_f32_e32 v49, v49
	v_add_f32_e32 v245, v48, v245
	v_cvt_pk_bf16_f32 v216, v34, v35
	v_cvt_pk_bf16_f32 v217, v36, v37
	v_cvt_pk_bf16_f32 v218, v38, v39
	v_cvt_pk_bf16_f32 v219, v40, v41
	s_waitcnt lgkmcnt(2)
	s_nop 0
	v_mfma_f32_32x32x16_bf16 v[18:33], v[216:219], v[190:193], v[18:33]
	v_mfma_f32_32x32x16_bf16 v[2:17], v[216:219], v[194:197], v[2:17]
	v_cvt_pk_bf16_f32 v224, v42, v43
	v_cvt_pk_bf16_f32 v225, v44, v45
	v_cvt_pk_bf16_f32 v226, v46, v47
	v_cvt_pk_bf16_f32 v227, v48, v49
	s_waitcnt lgkmcnt(0)
	s_nop 0
	v_mfma_f32_32x32x16_bf16 v[18:33], v[224:227], v[198:201], v[18:33]
	v_mfma_f32_32x32x16_bf16 v[2:17], v[224:227], v[212:215], v[2:17]
	v_add_f32_e32 v246, v49, v246
	v_add_f32_e32 v245, v245, v246
	s_nop 0
	v_add_f32_e32 v0, v0, v245

; #define PG8_STAGE(bufoff, gbase, voff) do { _Pragma("unroll") for (int _i = 0; _i < 2; ++_i) \
;         __builtin_amdgcn_global_load_lds((const unsigned*)((const char*)(gbase) + (voff)[_i]), (PG8_LAS unsigned*)(lds + (bufoff) + ldsw + _i * 8192), 16, 0, 0); } while (0)
; #define PG8_LDA(dst, b, h) do { _Pragma("unroll") for (int m = 0; m < 4; ++m) _Pragma("unroll") for (int k = 0; k < 2; ++k) dst[m][k] = *(const PG8_LAS bf16x8*)(lds + PG8_SA(b, h) + aoff + m * 2048 + k * 1024); } while (0)
; #define PG8_LDB(dst, b, h) do { _Pragma("unroll") for (int n = 0; n < 2; ++n) _Pragma("unroll") for (int k = 0; k < 2; ++k) dst[n][k] = *(const PG8_LAS bf16x8*)(lds + PG8_SB(b, h) + boff + n * 2048 + k * 1024); } while (0)
; #define PG8_WAIT_V(n) asm volatile("s_waitcnt vmcnt(" #n ")" ::: "memory")
; #define PG8_WAIT_L(n) asm volatile("s_waitcnt lgkmcnt(" #n ")" ::: "memory")
; #define PG8_BAR __builtin_amdgcn_s_barrier()
; #define PG8_SCHED __builtin_amdgcn_sched_barrier(0)
; template <class Epi, class Sched, bool ALIGN_EPI = false, bool SP2 = false>
; __device__ __forceinline__ void gemm_phase(PG8_LAS unsigned char* lds, const Gemm g, const Sched& S, const Epi& E, const int wid_in) {
;     ...
;         const bool has_next = S.next(ui + 1, nxt);
;         const char* nA = has_next ? (const char*)g.A + (size_t)nxt.pm * tstep : cA; const char* nB = has_next ? (const char*)g.Bt + (size_t)nxt.pn * tstep : cB;
; #pragma unroll 1
;         for (int t = 0; t < nt; t += 2) {
;             const bool last = (t == nt - 2);
;             const char* a1 = cA + (size_t)(t + 1) * kstep;
;             const char* a2 = last ? nA : cA + (size_t)(t + 2) * kstep; const char* b2 = last ? nB : cB + (size_t)(t + 2) * kstep;
;             const char* a3 = a2 + kstep; const char* b3 = b2 + kstep;
;             if (last && has_next) S.a_ready(nxt);
;             if constexpr (SP2) {
;             PG8_LDB(B0, 0, 0); PG8_LDB(B1, 0, 1); PG8_SCHED; PG8_LDA(At, 0, 0); PG8_STAGE(PG8_SA(1, 1), a1 + hstep, voffA);
;             PG8_WAIT_V(8); PG8_WAIT_L(0); PG8_BAR; PG8_MMA(0, 0, At, B0); PG8_MMA(0, 1, At, B1); PG8_BAR; PG8_SCHED;
;             PG8_LDA(At, 0, 1); PG8_STAGE(PG8_SB(0, 0), b2, voffB); PG8_STAGE(PG8_SB(0, 1), b2 + hstep, voffB); PG8_STAGE(PG8_SA(0, 0), a2, voffA);
;             PG8_WAIT_V(8); PG8_WAIT_L(0); PG8_BAR; PG8_MMA(1, 0, At, B0); PG8_MMA(1, 1, At, B1); PG8_BAR; PG8_SCHED;
.LBB0_536:
	s_ashr_i32 s43, s42, 31
	s_lshl_b64 s[22:23], s[42:43], 19
	v_readlane_b32 s2, v240, 12
	s_add_u32 s44, s2, s22
	v_readlane_b32 s2, v240, 13
	s_addc_u32 s45, s2, s23
	s_and_b64 s[22:23], s[40:41], exec
	s_cselect_b32 s43, s45, s49
	s_cselect_b32 s57, s44, s48
	s_ashr_i32 s39, s38, 31
	s_lshl_b64 s[22:23], s[38:39], 19
	v_readlane_b32 s2, v243, 22
	s_add_u32 s46, s2, s22
	v_readlane_b32 s2, v243, 23
	s_addc_u32 s47, s2, s23
	s_and_b64 s[22:23], s[40:41], exec
	s_cselect_b32 s16, s47, s51
	s_cselect_b32 s39, s46, s50
	s_add_u32 s48, s48, 0x40080
	s_addc_u32 s49, s49, 0
	s_add_u32 s58, s50, 0x100
	s_addc_u32 s59, s51, 0
	s_mov_b32 s60, -2
	s_add_u32 s2, s48, 0xfffc0080
	s_addc_u32 s8, s49, -1
	s_add_i32 s9, 0, 0x10000
	s_cmp_eq_u32 s60, 12
	s_cselect_b32 s53, s43, s8
	s_cselect_b32 s52, s57, s2
	v_add_u32_e32 v140, s9, v142
	s_cselect_b32 s51, s16, s59
	s_cselect_b32 s50, s39, s58
	s_add_i32 s2, 0, 0x14000
	ds_read_b128 v[144:147], v140
	ds_read_b128 v[148:151], v140 offset:1024
	ds_read_b128 v[152:155], v140 offset:2048
	ds_read_b128 v[156:159], v140 offset:3072
	v_add_u32_e32 v140, s2, v142
	ds_read_b128 v[160:163], v140
	ds_read_b128 v[164:167], v140 offset:1024
	ds_read_b128 v[168:171], v140 offset:2048
	ds_read_b128 v[172:175], v140 offset:3072
	v_lshl_add_u64 v[140:141], s[48:49], 0, v[136:137]
	s_add_i32 m0, s4, 0xc000
	ds_read_b128 v[190:193], v143
	ds_read_b128 v[194:197], v143 offset:1024
	ds_read_b128 v[198:201], v143 offset:2048
	ds_read_b128 v[212:215], v143 offset:3072
	ds_read_b128 v[216:219], v143 offset:4096
	ds_read_b128 v[220:223], v143 offset:5120
	ds_read_b128 v[224:227], v143 offset:6144
	ds_read_b128 v[228:231], v143 offset:7168
	global_load_lds_dwordx4 v[140:141], off
	v_lshl_add_u64 v[140:141], s[48:49], 0, v[138:139]
	s_add_i32 m0, s4, 0xe000
	s_nop 0
	global_load_lds_dwordx4 v[140:141], off
	s_waitcnt vmcnt(8)
	s_waitcnt lgkmcnt(0)
	s_barrier
	s_setprio 1
	s_waitcnt lgkmcnt(0)
	v_mfma_f32_16x16x32_bf16 v[126:129], v[144:147], v[190:193], 0
	v_mfma_f32_16x16x32_bf16 v[122:125], v[152:155], v[190:193], 0
	v_mfma_f32_16x16x32_bf16 v[118:121], v[144:147], v[198:201], 0
	v_mfma_f32_16x16x32_bf16 v[110:113], v[152:155], v[198:201], 0
	v_mfma_f32_16x16x32_bf16 v[102:105], v[144:147], v[216:219], 0
	v_mfma_f32_16x16x32_bf16 v[94:97], v[152:155], v[216:219], 0
	v_mfma_f32_16x16x32_bf16 v[82:85], v[144:147], v[224:227], 0
	v_mfma_f32_16x16x32_bf16 v[74:77], v[152:155], v[224:227], 0
	v_mfma_f32_16x16x32_bf16 v[126:129], v[148:151], v[194:197], v[126:129]
	v_mfma_f32_16x16x32_bf16 v[122:125], v[156:159], v[194:197], v[122:125]
	v_mfma_f32_16x16x32_bf16 v[118:121], v[148:151], v[212:215], v[118:121]
	v_mfma_f32_16x16x32_bf16 v[110:113], v[156:159], v[212:215], v[110:113]
	v_mfma_f32_16x16x32_bf16 v[102:105], v[148:151], v[220:223], v[102:105]
	v_mfma_f32_16x16x32_bf16 v[94:97], v[156:159], v[220:223], v[94:97]
	v_mfma_f32_16x16x32_bf16 v[82:85], v[148:151], v[228:231], v[82:85]
	v_mfma_f32_16x16x32_bf16 v[74:77], v[156:159], v[228:231], v[74:77]
	s_setprio 0
	s_setprio 1
	v_mfma_f32_16x16x32_bf16 v[114:117], v[160:163], v[190:193], 0
	v_mfma_f32_16x16x32_bf16 v[106:109], v[168:171], v[190:193], 0
	v_mfma_f32_16x16x32_bf16 v[98:101], v[160:163], v[198:201], 0
	v_mfma_f32_16x16x32_bf16 v[90:93], v[168:171], v[198:201], 0
	v_mfma_f32_16x16x32_bf16 v[86:89], v[160:163], v[216:219], 0
	v_mfma_f32_16x16x32_bf16 v[78:81], v[168:171], v[216:219], 0
	v_mfma_f32_16x16x32_bf16 v[70:73], v[160:163], v[224:227], 0
	v_mfma_f32_16x16x32_bf16 v[66:69], v[168:171], v[224:227], 0
	v_mfma_f32_16x16x32_bf16 v[114:117], v[164:167], v[194:197], v[114:117]
	v_mfma_f32_16x16x32_bf16 v[106:109], v[172:175], v[194:197], v[106:109]
	v_mfma_f32_16x16x32_bf16 v[98:101], v[164:167], v[212:215], v[98:101]
	v_mfma_f32_16x16x32_bf16 v[90:93], v[172:175], v[212:215], v[90:93]
	v_mfma_f32_16x16x32_bf16 v[86:89], v[164:167], v[220:223], v[86:89]
	v_mfma_f32_16x16x32_bf16 v[78:81], v[172:175], v[220:223], v[78:81]
	v_mfma_f32_16x16x32_bf16 v[70:73], v[164:167], v[228:231], v[70:73]
	v_mfma_f32_16x16x32_bf16 v[66:69], v[172:175], v[228:231], v[66:69]
	s_setprio 0
	s_barrier
	s_add_i32 s8, s9, s3
	v_lshl_add_u64 v[140:141], s[50:51], 0, v[0:1]
	s_mov_b32 m0, s8
	ds_read_b128 v[190:193], v143 offset:16384
	ds_read_b128 v[194:197], v143 offset:17408
	ds_read_b128 v[198:201], v143 offset:18432
	ds_read_b128 v[212:215], v143 offset:19456
	ds_read_b128 v[216:219], v143 offset:20480
	ds_read_b128 v[220:223], v143 offset:21504
	ds_read_b128 v[224:227], v143 offset:22528
	ds_read_b128 v[228:231], v143 offset:23552
	global_load_lds_dwordx4 v[140:141], off
	s_add_i32 m0, s8, 0x2000
	s_add_u32 s22, s50, 0x40000
	v_lshl_add_u64 v[176:177], s[50:51], 0, v[130:131]
	s_addc_u32 s23, s51, 0
	s_add_i32 s2, s2, s3
	global_load_lds_dwordx4 v[176:177], off
	v_lshl_add_u64 v[232:233], s[22:23], 0, v[0:1]
	s_mov_b32 m0, s2
	v_lshl_add_u64 v[234:235], s[52:53], 0, v[132:133]
	global_load_lds_dwordx4 v[232:233], off
	v_lshl_add_u64 v[232:233], s[22:23], 0, v[130:131]
	s_add_i32 m0, s2, 0x2000
	s_nop 0
	global_load_lds_dwordx4 v[232:233], off
	v_lshl_add_u64 v[232:233], s[52:53], 0, v[134:135]
	s_mov_b32 m0, s4
	s_nop 0
	global_load_lds_dwordx4 v[232:233], off
	s_mov_b32 m0, s5
	s_nop 0
	global_load_lds_dwordx4 v[234:235], off
	s_waitcnt vmcnt(8)
	s_waitcnt lgkmcnt(0)
	s_barrier
; #define PG8_STAGE(bufoff, gbase, voff) do { _Pragma("unroll") for (int _i = 0; _i < 2; ++_i) \
;         __builtin_amdgcn_global_load_lds((const unsigned*)((const char*)(gbase) + (voff)[_i]), (PG8_LAS unsigned*)(lds + (bufoff) + ldsw + _i * 8192), 16, 0, 0); } while (0)
; #define PG8_LDA(dst, b, h) do { _Pragma("unroll") for (int m = 0; m < 4; ++m) _Pragma("unroll") for (int k = 0; k < 2; ++k) dst[m][k] = *(const PG8_LAS bf16x8*)(lds + PG8_SA(b, h) + aoff + m * 2048 + k * 1024); } while (0)
; #define PG8_LDB(dst, b, h) do { _Pragma("unroll") for (int n = 0; n < 2; ++n) _Pragma("unroll") for (int k = 0; k < 2; ++k) dst[n][k] = *(const PG8_LAS bf16x8*)(lds + PG8_SB(b, h) + boff + n * 2048 + k * 1024); } while (0)
; #define PG8_MMA(ai, bj, At, Bt) do { __builtin_amdgcn_s_setprio(1); _Pragma("unroll") for (int m = 0; m < 4; ++m) _Pragma("unroll") for (int n = 0; n < 2; ++n) _Pragma("unroll") for (int k = 0; k < 2; ++k) \
;         acc[ai][bj][m][n] = __builtin_amdgcn_mfma_f32_16x16x32_bf16(Bt[n][k], At[m][k], acc[ai][bj][m][n], 0, 0, 0); __builtin_amdgcn_s_setprio(0); } while (0)
; #define PG8_WAIT_V(n) asm volatile("s_waitcnt vmcnt(" #n ")" ::: "memory")
; #define PG8_WAIT_L(n) asm volatile("s_waitcnt lgkmcnt(" #n ")" ::: "memory")
; #define PG8_BAR __builtin_amdgcn_s_barrier()
; #define PG8_SCHED __builtin_amdgcn_sched_barrier(0)
; template <class Epi, class Sched, bool ALIGN_EPI = false, bool SP2 = false>
; __device__ __forceinline__ void gemm_phase(PG8_LAS unsigned char* lds, const Gemm g, const Sched& S, const Epi& E, const int wid_in) {
;     ...
;             PG8_WAIT_V(8); PG8_WAIT_L(0); PG8_BAR; PG8_MMA(1, 0, At, B0); PG8_MMA(1, 1, At, B1); PG8_BAR; PG8_SCHED;
;             PG8_LDB(B0, 1, 0); PG8_LDB(B1, 1, 1); PG8_SCHED; PG8_LDA(At, 1, 0); PG8_STAGE(PG8_SA(0, 1), a2 + hstep, voffA);
;             PG8_WAIT_V(8); PG8_WAIT_L(0); PG8_BAR; PG8_MMA(0, 0, At, B0); PG8_MMA(0, 1, At, B1); PG8_BAR; PG8_SCHED;
	s_setprio 1
	s_waitcnt lgkmcnt(0)
	v_mfma_f32_16x16x32_bf16 v[62:65], v[144:147], v[190:193], 0
	v_mfma_f32_16x16x32_bf16 v[58:61], v[152:155], v[190:193], 0
	v_mfma_f32_16x16x32_bf16 v[54:57], v[144:147], v[198:201], 0
	v_mfma_f32_16x16x32_bf16 v[46:49], v[152:155], v[198:201], 0
	v_mfma_f32_16x16x32_bf16 v[38:41], v[144:147], v[216:219], 0
	v_mfma_f32_16x16x32_bf16 v[30:33], v[152:155], v[216:219], 0
	v_mfma_f32_16x16x32_bf16 v[22:25], v[144:147], v[224:227], 0
	v_mfma_f32_16x16x32_bf16 v[14:17], v[152:155], v[224:227], 0
	v_mfma_f32_16x16x32_bf16 v[62:65], v[148:151], v[194:197], v[62:65]
	v_mfma_f32_16x16x32_bf16 v[58:61], v[156:159], v[194:197], v[58:61]
	v_mfma_f32_16x16x32_bf16 v[54:57], v[148:151], v[212:215], v[54:57]
	v_mfma_f32_16x16x32_bf16 v[46:49], v[156:159], v[212:215], v[46:49]
	v_mfma_f32_16x16x32_bf16 v[38:41], v[148:151], v[220:223], v[38:41]
	v_mfma_f32_16x16x32_bf16 v[30:33], v[156:159], v[220:223], v[30:33]
	v_mfma_f32_16x16x32_bf16 v[22:25], v[148:151], v[228:231], v[22:25]
	v_mfma_f32_16x16x32_bf16 v[14:17], v[156:159], v[228:231], v[14:17]
	s_setprio 0
	s_setprio 1
	v_mfma_f32_16x16x32_bf16 v[50:53], v[160:163], v[190:193], 0
	v_mfma_f32_16x16x32_bf16 v[42:45], v[168:171], v[190:193], 0
	v_mfma_f32_16x16x32_bf16 v[34:37], v[160:163], v[198:201], 0
	v_mfma_f32_16x16x32_bf16 v[26:29], v[168:171], v[198:201], 0
	v_mfma_f32_16x16x32_bf16 v[18:21], v[160:163], v[216:219], 0
	v_mfma_f32_16x16x32_bf16 v[10:13], v[168:171], v[216:219], 0
	v_mfma_f32_16x16x32_bf16 v[6:9], v[160:163], v[224:227], 0
	v_mfma_f32_16x16x32_bf16 v[2:5], v[168:171], v[224:227], 0
	v_mfma_f32_16x16x32_bf16 v[50:53], v[164:167], v[194:197], v[50:53]
	v_mfma_f32_16x16x32_bf16 v[42:45], v[172:175], v[194:197], v[42:45]
	v_mfma_f32_16x16x32_bf16 v[34:37], v[164:167], v[212:215], v[34:37]
	v_mfma_f32_16x16x32_bf16 v[26:29], v[172:175], v[212:215], v[26:29]
	v_mfma_f32_16x16x32_bf16 v[18:21], v[164:167], v[220:223], v[18:21]
	v_mfma_f32_16x16x32_bf16 v[10:13], v[172:175], v[220:223], v[10:13]
	v_mfma_f32_16x16x32_bf16 v[6:9], v[164:167], v[228:231], v[6:9]
	v_mfma_f32_16x16x32_bf16 v[2:5], v[172:175], v[228:231], v[2:5]
	s_setprio 0
	s_barrier
	s_add_i32 s2, 0, 0x18000
	s_add_i32 s8, 0, 0x1c000
	v_add_u32_e32 v156, s2, v142
	v_add_u32_e32 v172, s8, v142
	ds_read_b128 v[144:147], v156
	ds_read_b128 v[148:151], v156 offset:1024
	ds_read_b128 v[152:155], v156 offset:2048
	ds_read_b128 v[156:159], v156 offset:3072
	ds_read_b128 v[160:163], v172
	ds_read_b128 v[164:167], v172 offset:1024
	ds_read_b128 v[168:171], v172 offset:2048
	ds_read_b128 v[172:175], v172 offset:3072
	s_add_u32 s22, s52, 0x40000
	s_addc_u32 s23, s53, 0
	s_mov_b32 m0, s12
	v_lshl_add_u64 v[236:237], s[22:23], 0, v[134:135]
	ds_read_b128 v[190:193], v143 offset:32768
	ds_read_b128 v[194:197], v143 offset:33792
	ds_read_b128 v[198:201], v143 offset:34816
	ds_read_b128 v[212:215], v143 offset:35840
	ds_read_b128 v[216:219], v143 offset:36864
	ds_read_b128 v[220:223], v143 offset:37888
	ds_read_b128 v[224:227], v143 offset:38912
	ds_read_b128 v[228:231], v143 offset:39936
	global_load_lds_dwordx4 v[236:237], off
	v_lshl_add_u64 v[236:237], s[22:23], 0, v[132:133]
	s_mov_b32 m0, s13
	s_nop 0
	global_load_lds_dwordx4 v[236:237], off
	s_waitcnt vmcnt(8)
	s_waitcnt lgkmcnt(0)
	s_barrier
	s_setprio 1
	s_waitcnt lgkmcnt(0)
	v_mfma_f32_16x16x32_bf16 v[126:129], v[144:147], v[190:193], v[126:129]
	v_mfma_f32_16x16x32_bf16 v[122:125], v[152:155], v[190:193], v[122:125]
	v_mfma_f32_16x16x32_bf16 v[118:121], v[144:147], v[198:201], v[118:121]
	v_mfma_f32_16x16x32_bf16 v[110:113], v[152:155], v[198:201], v[110:113]
	v_mfma_f32_16x16x32_bf16 v[102:105], v[144:147], v[216:219], v[102:105]
	v_mfma_f32_16x16x32_bf16 v[94:97], v[152:155], v[216:219], v[94:97]
	v_mfma_f32_16x16x32_bf16 v[82:85], v[144:147], v[224:227], v[82:85]
	v_mfma_f32_16x16x32_bf16 v[74:77], v[152:155], v[224:227], v[74:77]
	v_mfma_f32_16x16x32_bf16 v[126:129], v[148:151], v[194:197], v[126:129]
	v_mfma_f32_16x16x32_bf16 v[122:125], v[156:159], v[194:197], v[122:125]
	v_mfma_f32_16x16x32_bf16 v[118:121], v[148:151], v[212:215], v[118:121]
	v_mfma_f32_16x16x32_bf16 v[110:113], v[156:159], v[212:215], v[110:113]
	v_mfma_f32_16x16x32_bf16 v[102:105], v[148:151], v[220:223], v[102:105]
	v_mfma_f32_16x16x32_bf16 v[94:97], v[156:159], v[220:223], v[94:97]
	v_mfma_f32_16x16x32_bf16 v[82:85], v[148:151], v[228:231], v[82:85]
	v_mfma_f32_16x16x32_bf16 v[74:77], v[156:159], v[228:231], v[74:77]
	s_setprio 0
	s_setprio 1
	v_mfma_f32_16x16x32_bf16 v[114:117], v[160:163], v[190:193], v[114:117]
	v_mfma_f32_16x16x32_bf16 v[106:109], v[168:171], v[190:193], v[106:109]
	v_mfma_f32_16x16x32_bf16 v[98:101], v[160:163], v[198:201], v[98:101]
	v_mfma_f32_16x16x32_bf16 v[90:93], v[168:171], v[198:201], v[90:93]
	v_mfma_f32_16x16x32_bf16 v[86:89], v[160:163], v[216:219], v[86:89]
	v_mfma_f32_16x16x32_bf16 v[78:81], v[168:171], v[216:219], v[78:81]
	v_mfma_f32_16x16x32_bf16 v[70:73], v[160:163], v[224:227], v[70:73]
	v_mfma_f32_16x16x32_bf16 v[66:69], v[168:171], v[224:227], v[66:69]
	v_mfma_f32_16x16x32_bf16 v[114:117], v[164:167], v[194:197], v[114:117]
	v_mfma_f32_16x16x32_bf16 v[106:109], v[172:175], v[194:197], v[106:109]
	v_mfma_f32_16x16x32_bf16 v[98:101], v[164:167], v[212:215], v[98:101]
	v_mfma_f32_16x16x32_bf16 v[90:93], v[172:175], v[212:215], v[90:93]
	v_mfma_f32_16x16x32_bf16 v[86:89], v[164:167], v[220:223], v[86:89]
	v_mfma_f32_16x16x32_bf16 v[78:81], v[172:175], v[220:223], v[78:81]
	v_mfma_f32_16x16x32_bf16 v[70:73], v[164:167], v[228:231], v[70:73]
	v_mfma_f32_16x16x32_bf16 v[66:69], v[172:175], v[228:231], v[66:69]
	s_setprio 0
	s_barrier
; #define PG8_STAGE(bufoff, gbase, voff) do { _Pragma("unroll") for (int _i = 0; _i < 2; ++_i) \
;         __builtin_amdgcn_global_load_lds((const unsigned*)((const char*)(gbase) + (voff)[_i]), (PG8_LAS unsigned*)(lds + (bufoff) + ldsw + _i * 8192), 16, 0, 0); } while (0)
; #define PG8_LDA(dst, b, h) do { _Pragma("unroll") for (int m = 0; m < 4; ++m) _Pragma("unroll") for (int k = 0; k < 2; ++k) dst[m][k] = *(const PG8_LAS bf16x8*)(lds + PG8_SA(b, h) + aoff + m * 2048 + k * 1024); } while (0)
; #define PG8_MMA(ai, bj, At, Bt) do { __builtin_amdgcn_s_setprio(1); _Pragma("unroll") for (int m = 0; m < 4; ++m) _Pragma("unroll") for (int n = 0; n < 2; ++n) _Pragma("unroll") for (int k = 0; k < 2; ++k) \
;         acc[ai][bj][m][n] = __builtin_amdgcn_mfma_f32_16x16x32_bf16(Bt[n][k], At[m][k], acc[ai][bj][m][n], 0, 0, 0); __builtin_amdgcn_s_setprio(0); } while (0)
; #define PG8_WAIT_V(n) asm volatile("s_waitcnt vmcnt(" #n ")" ::: "memory")
; #define PG8_WAIT_L(n) asm volatile("s_waitcnt lgkmcnt(" #n ")" ::: "memory")
; #define PG8_BAR __builtin_amdgcn_s_barrier()
; #define PG8_SCHED __builtin_amdgcn_sched_barrier(0)
; template <class Epi, class Sched, bool ALIGN_EPI = false, bool SP2 = false>
; __device__ __forceinline__ void gemm_phase(PG8_LAS unsigned char* lds, const Gemm g, const Sched& S, const Epi& E, const int wid_in) {
;     ...
;         for (int t = 0; t < nt; t += 2) {
;     ...
;             PG8_LDA(At, 1, 1); PG8_STAGE(PG8_SB(1, 0), b3, voffB); PG8_STAGE(PG8_SB(1, 1), b3 + hstep, voffB); PG8_STAGE(PG8_SA(1, 0), a3, voffA);
;             PG8_WAIT_V(8); PG8_WAIT_L(0); PG8_BAR; PG8_MMA(1, 0, At, B0); PG8_MMA(1, 1, At, B1); PG8_BAR; PG8_SCHED;
	s_add_i32 s2, s2, s3
	v_lshl_add_u64 v[140:141], v[140:141], 0, s[64:65]
	s_mov_b32 m0, s2
	ds_read_b128 v[190:193], v143 offset:49152
	ds_read_b128 v[194:197], v143 offset:50176
	ds_read_b128 v[198:201], v143 offset:51200
	ds_read_b128 v[212:215], v143 offset:52224
	ds_read_b128 v[216:219], v143 offset:53248
	ds_read_b128 v[220:223], v143 offset:54272
	ds_read_b128 v[224:227], v143 offset:55296
	ds_read_b128 v[228:231], v143 offset:56320
	global_load_lds_dwordx4 v[140:141], off
	s_add_i32 m0, s2, 0x2000
	s_add_u32 s22, s50, 0x40080
	v_lshl_add_u64 v[140:141], v[176:177], 0, s[64:65]
	s_addc_u32 s23, s51, 0
	s_add_i32 s2, s8, s3
	global_load_lds_dwordx4 v[140:141], off
	v_lshl_add_u64 v[140:141], s[22:23], 0, v[0:1]
	s_mov_b32 m0, s2
	s_nop 0
	global_load_lds_dwordx4 v[140:141], off
	v_lshl_add_u64 v[140:141], s[22:23], 0, v[130:131]
	s_add_i32 m0, s2, 0x2000
	s_nop 0
	global_load_lds_dwordx4 v[140:141], off
	v_lshl_add_u64 v[140:141], v[232:233], 0, s[64:65]
	s_mov_b32 m0, s36
	s_nop 0
	global_load_lds_dwordx4 v[140:141], off
	v_lshl_add_u64 v[140:141], v[234:235], 0, s[64:65]
	s_mov_b32 m0, s37
	s_nop 0
	global_load_lds_dwordx4 v[140:141], off
	s_waitcnt vmcnt(8)
	s_waitcnt lgkmcnt(0)
	s_barrier
	s_setprio 1
	s_waitcnt lgkmcnt(0)
	v_mfma_f32_16x16x32_bf16 v[62:65], v[144:147], v[190:193], v[62:65]
	v_mfma_f32_16x16x32_bf16 v[58:61], v[152:155], v[190:193], v[58:61]
	v_mfma_f32_16x16x32_bf16 v[54:57], v[144:147], v[198:201], v[54:57]
	v_mfma_f32_16x16x32_bf16 v[46:49], v[152:155], v[198:201], v[46:49]
	v_mfma_f32_16x16x32_bf16 v[38:41], v[144:147], v[216:219], v[38:41]
	v_mfma_f32_16x16x32_bf16 v[30:33], v[152:155], v[216:219], v[30:33]
	v_mfma_f32_16x16x32_bf16 v[22:25], v[144:147], v[224:227], v[22:25]
	v_mfma_f32_16x16x32_bf16 v[14:17], v[152:155], v[224:227], v[14:17]
	v_mfma_f32_16x16x32_bf16 v[62:65], v[148:151], v[194:197], v[62:65]
	v_mfma_f32_16x16x32_bf16 v[58:61], v[156:159], v[194:197], v[58:61]
	v_mfma_f32_16x16x32_bf16 v[54:57], v[148:151], v[212:215], v[54:57]
	v_mfma_f32_16x16x32_bf16 v[46:49], v[156:159], v[212:215], v[46:49]
	v_mfma_f32_16x16x32_bf16 v[38:41], v[148:151], v[220:223], v[38:41]
	v_mfma_f32_16x16x32_bf16 v[30:33], v[156:159], v[220:223], v[30:33]
	v_mfma_f32_16x16x32_bf16 v[22:25], v[148:151], v[228:231], v[22:25]
	v_mfma_f32_16x16x32_bf16 v[14:17], v[156:159], v[228:231], v[14:17]
	s_setprio 0
	s_setprio 1
	v_mfma_f32_16x16x32_bf16 v[50:53], v[160:163], v[190:193], v[50:53]
	v_mfma_f32_16x16x32_bf16 v[42:45], v[168:171], v[190:193], v[42:45]
	v_mfma_f32_16x16x32_bf16 v[34:37], v[160:163], v[198:201], v[34:37]
	v_mfma_f32_16x16x32_bf16 v[26:29], v[168:171], v[198:201], v[26:29]
	v_mfma_f32_16x16x32_bf16 v[18:21], v[160:163], v[216:219], v[18:21]
	v_mfma_f32_16x16x32_bf16 v[10:13], v[168:171], v[216:219], v[10:13]
	v_mfma_f32_16x16x32_bf16 v[6:9], v[160:163], v[224:227], v[6:9]
	v_mfma_f32_16x16x32_bf16 v[2:5], v[168:171], v[224:227], v[2:5]
	v_mfma_f32_16x16x32_bf16 v[50:53], v[164:167], v[194:197], v[50:53]
	v_mfma_f32_16x16x32_bf16 v[42:45], v[172:175], v[194:197], v[42:45]
	v_mfma_f32_16x16x32_bf16 v[34:37], v[164:167], v[212:215], v[34:37]
	v_mfma_f32_16x16x32_bf16 v[26:29], v[172:175], v[212:215], v[26:29]
	v_mfma_f32_16x16x32_bf16 v[18:21], v[164:167], v[220:223], v[18:21]
	v_mfma_f32_16x16x32_bf16 v[10:13], v[172:175], v[220:223], v[10:13]
	v_mfma_f32_16x16x32_bf16 v[6:9], v[164:167], v[228:231], v[6:9]
	v_mfma_f32_16x16x32_bf16 v[2:5], v[172:175], v[228:231], v[2:5]
	s_setprio 0
	s_barrier
	s_add_i32 s60, s60, 2
	s_add_u32 s48, s48, 0x100
	s_addc_u32 s49, s49, 0
	s_add_u32 s58, s58, 0x100
	s_addc_u32 s59, s59, 0
	s_cmp_gt_u32 s60, 13

; #define PG8_STAGE(bufoff, gbase, voff) do { _Pragma("unroll") for (int _i = 0; _i < 2; ++_i) \
;         __builtin_amdgcn_global_load_lds((const unsigned*)((const char*)(gbase) + (voff)[_i]), (PG8_LAS unsigned*)(lds + (bufoff) + ldsw + _i * 8192), 16, 0, 0); } while (0)
; #define PG8_LDA(dst, b, h) do { _Pragma("unroll") for (int m = 0; m < 4; ++m) _Pragma("unroll") for (int k = 0; k < 2; ++k) dst[m][k] = *(const PG8_LAS bf16x8*)(lds + PG8_SA(b, h) + aoff + m * 2048 + k * 1024); } while (0)
; #define PG8_LDB(dst, b, h) do { _Pragma("unroll") for (int n = 0; n < 2; ++n) _Pragma("unroll") for (int k = 0; k < 2; ++k) dst[n][k] = *(const PG8_LAS bf16x8*)(lds + PG8_SB(b, h) + boff + n * 2048 + k * 1024); } while (0)
; #define PG8_WAIT_V(n) asm volatile("s_waitcnt vmcnt(" #n ")" ::: "memory")
; #define PG8_WAIT_L(n) asm volatile("s_waitcnt lgkmcnt(" #n ")" ::: "memory")
; #define PG8_BAR __builtin_amdgcn_s_barrier()
; #define PG8_SCHED __builtin_amdgcn_sched_barrier(0)
; template <class Epi, class Sched, bool ALIGN_EPI = false, bool SP2 = false>
; __device__ __forceinline__ void gemm_phase(PG8_LAS unsigned char* lds, const Gemm g, const Sched& S, const Epi& E, const int wid_in) {
;     ...
;         const bool has_next = S.next(ui + 1, nxt);
;         const char* nA = has_next ? (const char*)g.A + (size_t)nxt.pm * tstep : cA; const char* nB = has_next ? (const char*)g.Bt + (size_t)nxt.pn * tstep : cB;
; #pragma unroll 1
;         for (int t = 0; t < nt; t += 2) {
;             const bool last = (t == nt - 2);
;             const char* a1 = cA + (size_t)(t + 1) * kstep;
;             const char* a2 = last ? nA : cA + (size_t)(t + 2) * kstep; const char* b2 = last ? nB : cB + (size_t)(t + 2) * kstep;
;             const char* a3 = a2 + kstep; const char* b3 = b2 + kstep;
;             if (last && has_next) S.a_ready(nxt);
;             if constexpr (SP2) {
;             PG8_LDB(B0, 0, 0); PG8_LDB(B1, 0, 1); PG8_SCHED; PG8_LDA(At, 0, 0); PG8_STAGE(PG8_SA(1, 1), a1 + hstep, voffA);
;             PG8_WAIT_V(8); PG8_WAIT_L(0); PG8_BAR; PG8_MMA(0, 0, At, B0); PG8_MMA(0, 1, At, B1); PG8_BAR; PG8_SCHED;
;             PG8_LDA(At, 0, 1); PG8_STAGE(PG8_SB(0, 0), b2, voffB); PG8_STAGE(PG8_SB(0, 1), b2 + hstep, voffB); PG8_STAGE(PG8_SA(0, 0), a2, voffA);
;             PG8_WAIT_V(8); PG8_WAIT_L(0); PG8_BAR; PG8_MMA(1, 0, At, B0); PG8_MMA(1, 1, At, B1); PG8_BAR; PG8_SCHED;
.LBB0_704:
	s_ashr_i32 s61, s60, 31
	s_lshl_b64 s[22:23], s[60:61], 19
	v_readlane_b32 s8, v243, 52
	v_readlane_b32 s9, v243, 53
	s_add_u32 s38, s8, s22
	s_addc_u32 s39, s9, s23
	s_and_b64 s[22:23], s[40:41], exec
	s_cselect_b32 s48, s39, s43
	s_cselect_b32 s49, s38, s42
	s_ashr_i32 s59, s58, 31
	s_lshl_b64 s[22:23], s[58:59], 19
	v_readlane_b32 s2, v243, 24
	s_add_u32 s52, s2, s22
	v_readlane_b32 s2, v243, 25
	s_addc_u32 s53, s2, s23
	s_and_b64 s[22:23], s[40:41], exec
	s_cselect_b32 s16, s53, s45
	s_cselect_b32 s59, s52, s44
	s_add_u32 s42, s42, 0x40080
	s_addc_u32 s43, s43, 0
	s_add_u32 s61, s44, 0x100
	s_addc_u32 s62, s45, 0
	s_mov_b32 vcc_lo, -2
	s_add_u32 s2, s42, 0xfffc0080
	s_addc_u32 s8, s43, -1
	s_add_i32 s9, 0, 0x10000
	s_cmp_eq_u32 vcc_lo, 12
	s_cselect_b32 s47, s48, s8
	s_cselect_b32 s46, s49, s2
	s_cselect_b32 s45, s16, s62
	s_cselect_b32 s44, s59, s61
	s_add_i32 s2, 0, 0x14000
	v_add_u32_e32 v142, s9, v211
	v_add_u32_e32 v158, s2, v211
	ds_read_b128 v[130:133], v142
	ds_read_b128 v[134:137], v142 offset:1024
	ds_read_b128 v[138:141], v142 offset:2048
	ds_read_b128 v[142:145], v142 offset:3072
	ds_read_b128 v[146:149], v158
	ds_read_b128 v[150:153], v158 offset:1024
	ds_read_b128 v[154:157], v158 offset:2048
	ds_read_b128 v[158:161], v158 offset:3072
	v_lshl_add_u64 v[200:201], s[42:43], 0, v[196:197]
	s_add_i32 m0, s12, 0xc000
	ds_read_b128 v[162:165], v212
	ds_read_b128 v[166:169], v212 offset:1024
	ds_read_b128 v[170:173], v212 offset:2048
	ds_read_b128 v[174:177], v212 offset:3072
	ds_read_b128 v[214:217], v212 offset:4096
	ds_read_b128 v[218:221], v212 offset:5120
	ds_read_b128 v[222:225], v212 offset:6144
	ds_read_b128 v[226:229], v212 offset:7168
	global_load_lds_dwordx4 v[200:201], off
	v_lshl_add_u64 v[200:201], s[42:43], 0, v[198:199]
	s_add_i32 m0, s12, 0xe000
	s_nop 0
	global_load_lds_dwordx4 v[200:201], off
	s_waitcnt vmcnt(8)
	s_waitcnt lgkmcnt(0)
	s_barrier
	s_setprio 1
	s_waitcnt lgkmcnt(0)
	v_mfma_f32_16x16x32_bf16 v[126:129], v[130:133], v[162:165], 0
	v_mfma_f32_16x16x32_bf16 v[94:97], v[138:141], v[162:165], 0
	v_mfma_f32_16x16x32_bf16 v[118:121], v[130:133], v[170:173], 0
	v_mfma_f32_16x16x32_bf16 v[86:89], v[138:141], v[170:173], 0
	v_mfma_f32_16x16x32_bf16 v[110:113], v[130:133], v[214:217], 0
	v_mfma_f32_16x16x32_bf16 v[78:81], v[138:141], v[214:217], 0
	v_mfma_f32_16x16x32_bf16 v[102:105], v[130:133], v[222:225], 0
	v_mfma_f32_16x16x32_bf16 v[70:73], v[138:141], v[222:225], 0
	v_mfma_f32_16x16x32_bf16 v[126:129], v[134:137], v[166:169], v[126:129]
	v_mfma_f32_16x16x32_bf16 v[94:97], v[142:145], v[166:169], v[94:97]
	v_mfma_f32_16x16x32_bf16 v[118:121], v[134:137], v[174:177], v[118:121]
	v_mfma_f32_16x16x32_bf16 v[86:89], v[142:145], v[174:177], v[86:89]
	v_mfma_f32_16x16x32_bf16 v[110:113], v[134:137], v[218:221], v[110:113]
	v_mfma_f32_16x16x32_bf16 v[78:81], v[142:145], v[218:221], v[78:81]
	v_mfma_f32_16x16x32_bf16 v[102:105], v[134:137], v[226:229], v[102:105]
	v_mfma_f32_16x16x32_bf16 v[70:73], v[142:145], v[226:229], v[70:73]
	s_setprio 0
	s_setprio 1
	v_mfma_f32_16x16x32_bf16 v[122:125], v[146:149], v[162:165], 0
	v_mfma_f32_16x16x32_bf16 v[90:93], v[154:157], v[162:165], 0
	v_mfma_f32_16x16x32_bf16 v[114:117], v[146:149], v[170:173], 0
	v_mfma_f32_16x16x32_bf16 v[82:85], v[154:157], v[170:173], 0
	v_mfma_f32_16x16x32_bf16 v[106:109], v[146:149], v[214:217], 0
	v_mfma_f32_16x16x32_bf16 v[74:77], v[154:157], v[214:217], 0
	v_mfma_f32_16x16x32_bf16 v[98:101], v[146:149], v[222:225], 0
	v_mfma_f32_16x16x32_bf16 v[66:69], v[154:157], v[222:225], 0
	v_mfma_f32_16x16x32_bf16 v[122:125], v[150:153], v[166:169], v[122:125]
	v_mfma_f32_16x16x32_bf16 v[90:93], v[158:161], v[166:169], v[90:93]
	v_mfma_f32_16x16x32_bf16 v[114:117], v[150:153], v[174:177], v[114:117]
	v_mfma_f32_16x16x32_bf16 v[82:85], v[158:161], v[174:177], v[82:85]
	v_mfma_f32_16x16x32_bf16 v[106:109], v[150:153], v[218:221], v[106:109]
	v_mfma_f32_16x16x32_bf16 v[74:77], v[158:161], v[218:221], v[74:77]
	v_mfma_f32_16x16x32_bf16 v[98:101], v[150:153], v[226:229], v[98:101]
	v_mfma_f32_16x16x32_bf16 v[66:69], v[158:161], v[226:229], v[66:69]
	s_setprio 0
	s_barrier
	s_add_i32 s8, s9, s3
	v_lshl_add_u64 v[200:201], s[44:45], 0, v[0:1]
	s_mov_b32 m0, s8
	ds_read_b128 v[162:165], v212 offset:16384
	ds_read_b128 v[166:169], v212 offset:17408
	ds_read_b128 v[170:173], v212 offset:18432
	ds_read_b128 v[174:177], v212 offset:19456
	ds_read_b128 v[214:217], v212 offset:20480
	ds_read_b128 v[218:221], v212 offset:21504
	ds_read_b128 v[222:225], v212 offset:22528
	ds_read_b128 v[226:229], v212 offset:23552
	global_load_lds_dwordx4 v[200:201], off
	s_add_i32 m0, s8, 0x2000
	s_add_u32 s22, s44, 0x40000
	v_lshl_add_u64 v[230:231], s[44:45], 0, v[194:195]
	s_addc_u32 s23, s45, 0
	s_add_i32 s2, s2, s3
	global_load_lds_dwordx4 v[230:231], off
	v_lshl_add_u64 v[232:233], s[22:23], 0, v[0:1]
	s_mov_b32 m0, s2
	v_lshl_add_u64 v[234:235], s[46:47], 0, v[192:193]
	global_load_lds_dwordx4 v[232:233], off
	v_lshl_add_u64 v[232:233], s[22:23], 0, v[194:195]
	s_add_i32 m0, s2, 0x2000
	s_nop 0
	global_load_lds_dwordx4 v[232:233], off
	v_lshl_add_u64 v[232:233], s[46:47], 0, v[190:191]
	s_mov_b32 m0, s12
	s_nop 0
	global_load_lds_dwordx4 v[232:233], off
	s_mov_b32 m0, s13
	s_nop 0
	global_load_lds_dwordx4 v[234:235], off
	s_waitcnt vmcnt(8)
	s_waitcnt lgkmcnt(0)
	s_barrier
; #define PG8_STAGE(bufoff, gbase, voff) do { _Pragma("unroll") for (int _i = 0; _i < 2; ++_i) \
;         __builtin_amdgcn_global_load_lds((const unsigned*)((const char*)(gbase) + (voff)[_i]), (PG8_LAS unsigned*)(lds + (bufoff) + ldsw + _i * 8192), 16, 0, 0); } while (0)
; #define PG8_LDA(dst, b, h) do { _Pragma("unroll") for (int m = 0; m < 4; ++m) _Pragma("unroll") for (int k = 0; k < 2; ++k) dst[m][k] = *(const PG8_LAS bf16x8*)(lds + PG8_SA(b, h) + aoff + m * 2048 + k * 1024); } while (0)
; #define PG8_LDB(dst, b, h) do { _Pragma("unroll") for (int n = 0; n < 2; ++n) _Pragma("unroll") for (int k = 0; k < 2; ++k) dst[n][k] = *(const PG8_LAS bf16x8*)(lds + PG8_SB(b, h) + boff + n * 2048 + k * 1024); } while (0)
; #define PG8_MMA(ai, bj, At, Bt) do { __builtin_amdgcn_s_setprio(1); _Pragma("unroll") for (int m = 0; m < 4; ++m) _Pragma("unroll") for (int n = 0; n < 2; ++n) _Pragma("unroll") for (int k = 0; k < 2; ++k) \
;         acc[ai][bj][m][n] = __builtin_amdgcn_mfma_f32_16x16x32_bf16(Bt[n][k], At[m][k], acc[ai][bj][m][n], 0, 0, 0); __builtin_amdgcn_s_setprio(0); } while (0)
; #define PG8_WAIT_V(n) asm volatile("s_waitcnt vmcnt(" #n ")" ::: "memory")
; #define PG8_WAIT_L(n) asm volatile("s_waitcnt lgkmcnt(" #n ")" ::: "memory")
; #define PG8_BAR __builtin_amdgcn_s_barrier()
; #define PG8_SCHED __builtin_amdgcn_sched_barrier(0)
; template <class Epi, class Sched, bool ALIGN_EPI = false, bool SP2 = false>
; __device__ __forceinline__ void gemm_phase(PG8_LAS unsigned char* lds, const Gemm g, const Sched& S, const Epi& E, const int wid_in) {
;     ...
;             PG8_WAIT_V(8); PG8_WAIT_L(0); PG8_BAR; PG8_MMA(1, 0, At, B0); PG8_MMA(1, 1, At, B1); PG8_BAR; PG8_SCHED;
;             PG8_LDB(B0, 1, 0); PG8_LDB(B1, 1, 1); PG8_SCHED; PG8_LDA(At, 1, 0); PG8_STAGE(PG8_SA(0, 1), a2 + hstep, voffA);
;             PG8_WAIT_V(8); PG8_WAIT_L(0); PG8_BAR; PG8_MMA(0, 0, At, B0); PG8_MMA(0, 1, At, B1); PG8_BAR; PG8_SCHED;
	s_setprio 1
	s_waitcnt lgkmcnt(0)
	v_mfma_f32_16x16x32_bf16 v[62:65], v[130:133], v[162:165], 0
	v_mfma_f32_16x16x32_bf16 v[30:33], v[138:141], v[162:165], 0
	v_mfma_f32_16x16x32_bf16 v[54:57], v[130:133], v[170:173], 0
	v_mfma_f32_16x16x32_bf16 v[22:25], v[138:141], v[170:173], 0
	v_mfma_f32_16x16x32_bf16 v[46:49], v[130:133], v[214:217], 0
	v_mfma_f32_16x16x32_bf16 v[14:17], v[138:141], v[214:217], 0
	v_mfma_f32_16x16x32_bf16 v[38:41], v[130:133], v[222:225], 0
	v_mfma_f32_16x16x32_bf16 v[6:9], v[138:141], v[222:225], 0
	v_mfma_f32_16x16x32_bf16 v[62:65], v[134:137], v[166:169], v[62:65]
	v_mfma_f32_16x16x32_bf16 v[30:33], v[142:145], v[166:169], v[30:33]
	v_mfma_f32_16x16x32_bf16 v[54:57], v[134:137], v[174:177], v[54:57]
	v_mfma_f32_16x16x32_bf16 v[22:25], v[142:145], v[174:177], v[22:25]
	v_mfma_f32_16x16x32_bf16 v[46:49], v[134:137], v[218:221], v[46:49]
	v_mfma_f32_16x16x32_bf16 v[14:17], v[142:145], v[218:221], v[14:17]
	v_mfma_f32_16x16x32_bf16 v[38:41], v[134:137], v[226:229], v[38:41]
	v_mfma_f32_16x16x32_bf16 v[6:9], v[142:145], v[226:229], v[6:9]
	s_setprio 0
	s_setprio 1
	v_mfma_f32_16x16x32_bf16 v[58:61], v[146:149], v[162:165], 0
	v_mfma_f32_16x16x32_bf16 v[26:29], v[154:157], v[162:165], 0
	v_mfma_f32_16x16x32_bf16 v[50:53], v[146:149], v[170:173], 0
	v_mfma_f32_16x16x32_bf16 v[18:21], v[154:157], v[170:173], 0
	v_mfma_f32_16x16x32_bf16 v[42:45], v[146:149], v[214:217], 0
	v_mfma_f32_16x16x32_bf16 v[10:13], v[154:157], v[214:217], 0
	v_mfma_f32_16x16x32_bf16 v[34:37], v[146:149], v[222:225], 0
	v_mfma_f32_16x16x32_bf16 v[2:5], v[154:157], v[222:225], 0
	v_mfma_f32_16x16x32_bf16 v[58:61], v[150:153], v[166:169], v[58:61]
	v_mfma_f32_16x16x32_bf16 v[26:29], v[158:161], v[166:169], v[26:29]
	v_mfma_f32_16x16x32_bf16 v[50:53], v[150:153], v[174:177], v[50:53]
	v_mfma_f32_16x16x32_bf16 v[18:21], v[158:161], v[174:177], v[18:21]
	v_mfma_f32_16x16x32_bf16 v[42:45], v[150:153], v[218:221], v[42:45]
	v_mfma_f32_16x16x32_bf16 v[10:13], v[158:161], v[218:221], v[10:13]
	v_mfma_f32_16x16x32_bf16 v[34:37], v[150:153], v[226:229], v[34:37]
	v_mfma_f32_16x16x32_bf16 v[2:5], v[158:161], v[226:229], v[2:5]
	s_setprio 0
	s_barrier
	s_add_i32 s2, 0, 0x18000
	s_add_i32 s8, 0, 0x1c000
	v_add_u32_e32 v142, s2, v211
	v_add_u32_e32 v158, s8, v211
	ds_read_b128 v[130:133], v142
	ds_read_b128 v[134:137], v142 offset:1024
	ds_read_b128 v[138:141], v142 offset:2048
	ds_read_b128 v[142:145], v142 offset:3072
	ds_read_b128 v[146:149], v158
	ds_read_b128 v[150:153], v158 offset:1024
	ds_read_b128 v[154:157], v158 offset:2048
	ds_read_b128 v[158:161], v158 offset:3072
	s_add_u32 s22, s46, 0x40000
	s_addc_u32 s23, s47, 0
	s_mov_b32 m0, s36
	v_lshl_add_u64 v[236:237], s[22:23], 0, v[190:191]
	ds_read_b128 v[162:165], v212 offset:32768
	ds_read_b128 v[166:169], v212 offset:33792
	ds_read_b128 v[170:173], v212 offset:34816
	ds_read_b128 v[174:177], v212 offset:35840
	ds_read_b128 v[214:217], v212 offset:36864
	ds_read_b128 v[218:221], v212 offset:37888
	ds_read_b128 v[222:225], v212 offset:38912
	ds_read_b128 v[226:229], v212 offset:39936
	global_load_lds_dwordx4 v[236:237], off
	v_lshl_add_u64 v[236:237], s[22:23], 0, v[192:193]
	s_mov_b32 m0, s37
	s_nop 0
	global_load_lds_dwordx4 v[236:237], off
	s_waitcnt vmcnt(8)
	s_waitcnt lgkmcnt(0)
	s_barrier
	s_setprio 1
	s_waitcnt lgkmcnt(0)
	v_mfma_f32_16x16x32_bf16 v[126:129], v[130:133], v[162:165], v[126:129]
	v_mfma_f32_16x16x32_bf16 v[94:97], v[138:141], v[162:165], v[94:97]
	v_mfma_f32_16x16x32_bf16 v[118:121], v[130:133], v[170:173], v[118:121]
	v_mfma_f32_16x16x32_bf16 v[86:89], v[138:141], v[170:173], v[86:89]
	v_mfma_f32_16x16x32_bf16 v[110:113], v[130:133], v[214:217], v[110:113]
	v_mfma_f32_16x16x32_bf16 v[78:81], v[138:141], v[214:217], v[78:81]
	v_mfma_f32_16x16x32_bf16 v[102:105], v[130:133], v[222:225], v[102:105]
	v_mfma_f32_16x16x32_bf16 v[70:73], v[138:141], v[222:225], v[70:73]
	v_mfma_f32_16x16x32_bf16 v[126:129], v[134:137], v[166:169], v[126:129]
	v_mfma_f32_16x16x32_bf16 v[94:97], v[142:145], v[166:169], v[94:97]
	v_mfma_f32_16x16x32_bf16 v[118:121], v[134:137], v[174:177], v[118:121]
	v_mfma_f32_16x16x32_bf16 v[86:89], v[142:145], v[174:177], v[86:89]
	v_mfma_f32_16x16x32_bf16 v[110:113], v[134:137], v[218:221], v[110:113]
	v_mfma_f32_16x16x32_bf16 v[78:81], v[142:145], v[218:221], v[78:81]
	v_mfma_f32_16x16x32_bf16 v[102:105], v[134:137], v[226:229], v[102:105]
	v_mfma_f32_16x16x32_bf16 v[70:73], v[142:145], v[226:229], v[70:73]
	s_setprio 0
	s_setprio 1
	v_mfma_f32_16x16x32_bf16 v[122:125], v[146:149], v[162:165], v[122:125]
	v_mfma_f32_16x16x32_bf16 v[90:93], v[154:157], v[162:165], v[90:93]
	v_mfma_f32_16x16x32_bf16 v[114:117], v[146:149], v[170:173], v[114:117]
	v_mfma_f32_16x16x32_bf16 v[82:85], v[154:157], v[170:173], v[82:85]
	v_mfma_f32_16x16x32_bf16 v[106:109], v[146:149], v[214:217], v[106:109]
	v_mfma_f32_16x16x32_bf16 v[74:77], v[154:157], v[214:217], v[74:77]
	v_mfma_f32_16x16x32_bf16 v[98:101], v[146:149], v[222:225], v[98:101]
	v_mfma_f32_16x16x32_bf16 v[66:69], v[154:157], v[222:225], v[66:69]
	v_mfma_f32_16x16x32_bf16 v[122:125], v[150:153], v[166:169], v[122:125]
	v_mfma_f32_16x16x32_bf16 v[90:93], v[158:161], v[166:169], v[90:93]
	v_mfma_f32_16x16x32_bf16 v[114:117], v[150:153], v[174:177], v[114:117]
	v_mfma_f32_16x16x32_bf16 v[82:85], v[158:161], v[174:177], v[82:85]
	v_mfma_f32_16x16x32_bf16 v[106:109], v[150:153], v[218:221], v[106:109]
	v_mfma_f32_16x16x32_bf16 v[74:77], v[158:161], v[218:221], v[74:77]
	v_mfma_f32_16x16x32_bf16 v[98:101], v[150:153], v[226:229], v[98:101]
	v_mfma_f32_16x16x32_bf16 v[66:69], v[158:161], v[226:229], v[66:69]
	s_setprio 0
	s_barrier
; #define PG8_STAGE(bufoff, gbase, voff) do { _Pragma("unroll") for (int _i = 0; _i < 2; ++_i) \
;         __builtin_amdgcn_global_load_lds((const unsigned*)((const char*)(gbase) + (voff)[_i]), (PG8_LAS unsigned*)(lds + (bufoff) + ldsw + _i * 8192), 16, 0, 0); } while (0)
; #define PG8_LDA(dst, b, h) do { _Pragma("unroll") for (int m = 0; m < 4; ++m) _Pragma("unroll") for (int k = 0; k < 2; ++k) dst[m][k] = *(const PG8_LAS bf16x8*)(lds + PG8_SA(b, h) + aoff + m * 2048 + k * 1024); } while (0)
; #define PG8_MMA(ai, bj, At, Bt) do { __builtin_amdgcn_s_setprio(1); _Pragma("unroll") for (int m = 0; m < 4; ++m) _Pragma("unroll") for (int n = 0; n < 2; ++n) _Pragma("unroll") for (int k = 0; k < 2; ++k) \
;         acc[ai][bj][m][n] = __builtin_amdgcn_mfma_f32_16x16x32_bf16(Bt[n][k], At[m][k], acc[ai][bj][m][n], 0, 0, 0); __builtin_amdgcn_s_setprio(0); } while (0)
; #define PG8_WAIT_V(n) asm volatile("s_waitcnt vmcnt(" #n ")" ::: "memory")
; #define PG8_WAIT_L(n) asm volatile("s_waitcnt lgkmcnt(" #n ")" ::: "memory")
; #define PG8_BAR __builtin_amdgcn_s_barrier()
; #define PG8_SCHED __builtin_amdgcn_sched_barrier(0)
; template <class Epi, class Sched, bool ALIGN_EPI = false, bool SP2 = false>
; __device__ __forceinline__ void gemm_phase(PG8_LAS unsigned char* lds, const Gemm g, const Sched& S, const Epi& E, const int wid_in) {
;     ...
;         for (int t = 0; t < nt; t += 2) {
;     ...
;             PG8_LDA(At, 1, 1); PG8_STAGE(PG8_SB(1, 0), b3, voffB); PG8_STAGE(PG8_SB(1, 1), b3 + hstep, voffB); PG8_STAGE(PG8_SA(1, 0), a3, voffA);
;             PG8_WAIT_V(8); PG8_WAIT_L(0); PG8_BAR; PG8_MMA(1, 0, At, B0); PG8_MMA(1, 1, At, B1); PG8_BAR; PG8_SCHED;
	s_add_i32 s2, s2, s3
	v_lshl_add_u64 v[200:201], v[200:201], 0, s[64:65]
	s_mov_b32 m0, s2
	ds_read_b128 v[162:165], v212 offset:49152
	ds_read_b128 v[166:169], v212 offset:50176
	ds_read_b128 v[170:173], v212 offset:51200
	ds_read_b128 v[174:177], v212 offset:52224
	ds_read_b128 v[214:217], v212 offset:53248
	ds_read_b128 v[218:221], v212 offset:54272
	ds_read_b128 v[222:225], v212 offset:55296
	ds_read_b128 v[226:229], v212 offset:56320
	global_load_lds_dwordx4 v[200:201], off
	s_add_i32 m0, s2, 0x2000
	s_add_u32 s22, s44, 0x40080
	v_lshl_add_u64 v[200:201], v[230:231], 0, s[64:65]
	s_addc_u32 s23, s45, 0
	s_add_i32 s2, s8, s3
	global_load_lds_dwordx4 v[200:201], off
	v_lshl_add_u64 v[200:201], s[22:23], 0, v[0:1]
	s_mov_b32 m0, s2
	s_nop 0
	global_load_lds_dwordx4 v[200:201], off
	v_lshl_add_u64 v[200:201], s[22:23], 0, v[194:195]
	s_add_i32 m0, s2, 0x2000
	s_nop 0
	global_load_lds_dwordx4 v[200:201], off
	v_lshl_add_u64 v[200:201], v[232:233], 0, s[64:65]
	s_mov_b32 m0, s78
	s_nop 0
	global_load_lds_dwordx4 v[200:201], off
	v_lshl_add_u64 v[200:201], v[234:235], 0, s[64:65]
	s_mov_b32 m0, s79
	s_nop 0
	global_load_lds_dwordx4 v[200:201], off
	s_waitcnt vmcnt(8)
	s_waitcnt lgkmcnt(0)
	s_barrier
	s_setprio 1
	s_waitcnt lgkmcnt(0)
	v_mfma_f32_16x16x32_bf16 v[62:65], v[130:133], v[162:165], v[62:65]
	v_mfma_f32_16x16x32_bf16 v[30:33], v[138:141], v[162:165], v[30:33]
	v_mfma_f32_16x16x32_bf16 v[54:57], v[130:133], v[170:173], v[54:57]
	v_mfma_f32_16x16x32_bf16 v[22:25], v[138:141], v[170:173], v[22:25]
	v_mfma_f32_16x16x32_bf16 v[46:49], v[130:133], v[214:217], v[46:49]
	v_mfma_f32_16x16x32_bf16 v[14:17], v[138:141], v[214:217], v[14:17]
	v_mfma_f32_16x16x32_bf16 v[38:41], v[130:133], v[222:225], v[38:41]
	v_mfma_f32_16x16x32_bf16 v[6:9], v[138:141], v[222:225], v[6:9]
	v_mfma_f32_16x16x32_bf16 v[62:65], v[134:137], v[166:169], v[62:65]
	v_mfma_f32_16x16x32_bf16 v[30:33], v[142:145], v[166:169], v[30:33]
	v_mfma_f32_16x16x32_bf16 v[54:57], v[134:137], v[174:177], v[54:57]
	v_mfma_f32_16x16x32_bf16 v[22:25], v[142:145], v[174:177], v[22:25]
	v_mfma_f32_16x16x32_bf16 v[46:49], v[134:137], v[218:221], v[46:49]
	v_mfma_f32_16x16x32_bf16 v[14:17], v[142:145], v[218:221], v[14:17]
	v_mfma_f32_16x16x32_bf16 v[38:41], v[134:137], v[226:229], v[38:41]
	v_mfma_f32_16x16x32_bf16 v[6:9], v[142:145], v[226:229], v[6:9]
	s_setprio 0
	s_setprio 1
	v_mfma_f32_16x16x32_bf16 v[58:61], v[146:149], v[162:165], v[58:61]
	v_mfma_f32_16x16x32_bf16 v[26:29], v[154:157], v[162:165], v[26:29]
	v_mfma_f32_16x16x32_bf16 v[50:53], v[146:149], v[170:173], v[50:53]
	v_mfma_f32_16x16x32_bf16 v[18:21], v[154:157], v[170:173], v[18:21]
	v_mfma_f32_16x16x32_bf16 v[42:45], v[146:149], v[214:217], v[42:45]
	v_mfma_f32_16x16x32_bf16 v[10:13], v[154:157], v[214:217], v[10:13]
	v_mfma_f32_16x16x32_bf16 v[34:37], v[146:149], v[222:225], v[34:37]
	v_mfma_f32_16x16x32_bf16 v[2:5], v[154:157], v[222:225], v[2:5]
	v_mfma_f32_16x16x32_bf16 v[58:61], v[150:153], v[166:169], v[58:61]
	v_mfma_f32_16x16x32_bf16 v[26:29], v[158:161], v[166:169], v[26:29]
	v_mfma_f32_16x16x32_bf16 v[50:53], v[150:153], v[174:177], v[50:53]
	v_mfma_f32_16x16x32_bf16 v[18:21], v[158:161], v[174:177], v[18:21]
	v_mfma_f32_16x16x32_bf16 v[42:45], v[150:153], v[218:221], v[42:45]
	v_mfma_f32_16x16x32_bf16 v[10:13], v[158:161], v[218:221], v[10:13]
	v_mfma_f32_16x16x32_bf16 v[34:37], v[150:153], v[226:229], v[34:37]
	v_mfma_f32_16x16x32_bf16 v[2:5], v[158:161], v[226:229], v[2:5]
	s_setprio 0
	s_barrier
	s_add_i32 vcc_lo, vcc_lo, 2
	s_add_u32 s42, s42, 0x100
	s_addc_u32 s43, s43, 0
	s_add_u32 s61, s61, 0x100
	s_addc_u32 s62, s62, 0
	s_cmp_gt_u32 vcc_lo, 13

; #define PG8_STAGE(bufoff, gbase, voff) do { _Pragma("unroll") for (int _i = 0; _i < 2; ++_i) \
;         __builtin_amdgcn_global_load_lds((const unsigned*)((const char*)(gbase) + (voff)[_i]), (PG8_LAS unsigned*)(lds + (bufoff) + ldsw + _i * 8192), 16, 0, 0); } while (0)
; #define PG8_LDA(dst, b, h) do { _Pragma("unroll") for (int m = 0; m < 4; ++m) _Pragma("unroll") for (int k = 0; k < 2; ++k) dst[m][k] = *(const PG8_LAS bf16x8*)(lds + PG8_SA(b, h) + aoff + m * 2048 + k * 1024); } while (0)
; #define PG8_LDB(dst, b, h) do { _Pragma("unroll") for (int n = 0; n < 2; ++n) _Pragma("unroll") for (int k = 0; k < 2; ++k) dst[n][k] = *(const PG8_LAS bf16x8*)(lds + PG8_SB(b, h) + boff + n * 2048 + k * 1024); } while (0)
; #define PG8_WAIT_V(n) asm volatile("s_waitcnt vmcnt(" #n ")" ::: "memory")
; #define PG8_WAIT_L(n) asm volatile("s_waitcnt lgkmcnt(" #n ")" ::: "memory")
; #define PG8_BAR __builtin_amdgcn_s_barrier()
; #define PG8_SCHED __builtin_amdgcn_sched_barrier(0)
; template <class Epi, class Sched, bool ALIGN_EPI = false, bool SP2 = false>
; __device__ __forceinline__ void gemm_phase(PG8_LAS unsigned char* lds, const Gemm g, const Sched& S, const Epi& E, const int wid_in) {
;     ...
;         const bool has_next = S.next(ui + 1, nxt);
;         const char* nA = has_next ? (const char*)g.A + (size_t)nxt.pm * tstep : cA; const char* nB = has_next ? (const char*)g.Bt + (size_t)nxt.pn * tstep : cB;
; #pragma unroll 1
;         for (int t = 0; t < nt; t += 2) {
;             const bool last = (t == nt - 2);
;             const char* a1 = cA + (size_t)(t + 1) * kstep;
;             const char* a2 = last ? nA : cA + (size_t)(t + 2) * kstep; const char* b2 = last ? nB : cB + (size_t)(t + 2) * kstep;
;             const char* a3 = a2 + kstep; const char* b3 = b2 + kstep;
;             if (last && has_next) S.a_ready(nxt);
;             if constexpr (SP2) {
;             PG8_LDB(B0, 0, 0); PG8_LDB(B1, 0, 1); PG8_SCHED; PG8_LDA(At, 0, 0); PG8_STAGE(PG8_SA(1, 1), a1 + hstep, voffA);
;             PG8_WAIT_V(8); PG8_WAIT_L(0); PG8_BAR; PG8_MMA(0, 0, At, B0); PG8_MMA(0, 1, At, B1); PG8_BAR; PG8_SCHED;
;             PG8_LDA(At, 0, 1); PG8_STAGE(PG8_SB(0, 0), b2, voffB); PG8_STAGE(PG8_SB(0, 1), b2 + hstep, voffB); PG8_STAGE(PG8_SA(0, 0), a2, voffA);
;             PG8_WAIT_V(8); PG8_WAIT_L(0); PG8_BAR; PG8_MMA(1, 0, At, B0); PG8_MMA(1, 1, At, B1); PG8_BAR; PG8_SCHED;
.LBB0_822:
	s_add_u32 s16, s46, 0x100
	s_addc_u32 s57, s47, 0
	s_mov_b32 s58, -2
	s_add_u32 s46, s44, 0x100
	s_addc_u32 s47, s45, 0
	s_add_i32 s2, 0, 0x10000
	s_cmp_eq_u32 s58, 40
	s_cselect_b32 s51, s41, s47
	s_cselect_b32 s50, s40, s46
	v_add_u32_e32 v140, s2, v142
	s_cselect_b32 s49, s43, s57
	s_cselect_b32 s48, s42, s16
	s_add_i32 s8, 0, 0x14000
	ds_read_b128 v[144:147], v140
	ds_read_b128 v[148:151], v140 offset:1024
	ds_read_b128 v[152:155], v140 offset:2048
	ds_read_b128 v[156:159], v140 offset:3072
	v_add_u32_e32 v140, s8, v142
	ds_read_b128 v[160:163], v140
	ds_read_b128 v[164:167], v140 offset:1024
	ds_read_b128 v[168:171], v140 offset:2048
	ds_read_b128 v[172:175], v140 offset:3072
	v_lshl_add_u64 v[140:141], s[44:45], 0, v[136:137]
	s_add_i32 m0, s4, 0xc000
	ds_read_b128 v[190:193], v143
	ds_read_b128 v[194:197], v143 offset:1024
	ds_read_b128 v[198:201], v143 offset:2048
	ds_read_b128 v[212:215], v143 offset:3072
	ds_read_b128 v[216:219], v143 offset:4096
	ds_read_b128 v[220:223], v143 offset:5120
	ds_read_b128 v[224:227], v143 offset:6144
	ds_read_b128 v[228:231], v143 offset:7168
	global_load_lds_dwordx4 v[140:141], off
	v_lshl_add_u64 v[140:141], s[44:45], 0, v[138:139]
	s_add_i32 m0, s4, 0xe000
	s_nop 0
	global_load_lds_dwordx4 v[140:141], off
	s_waitcnt vmcnt(8)
	s_waitcnt lgkmcnt(0)
	s_barrier
	s_setprio 1
	s_waitcnt lgkmcnt(0)
	v_mfma_f32_16x16x32_bf16 v[126:129], v[144:147], v[190:193], 0
	v_mfma_f32_16x16x32_bf16 v[122:125], v[152:155], v[190:193], 0
	v_mfma_f32_16x16x32_bf16 v[118:121], v[144:147], v[198:201], 0
	v_mfma_f32_16x16x32_bf16 v[110:113], v[152:155], v[198:201], 0
	v_mfma_f32_16x16x32_bf16 v[102:105], v[144:147], v[216:219], 0
	v_mfma_f32_16x16x32_bf16 v[94:97], v[152:155], v[216:219], 0
	v_mfma_f32_16x16x32_bf16 v[82:85], v[144:147], v[224:227], 0
	v_mfma_f32_16x16x32_bf16 v[74:77], v[152:155], v[224:227], 0
	v_mfma_f32_16x16x32_bf16 v[126:129], v[148:151], v[194:197], v[126:129]
	v_mfma_f32_16x16x32_bf16 v[122:125], v[156:159], v[194:197], v[122:125]
	v_mfma_f32_16x16x32_bf16 v[118:121], v[148:151], v[212:215], v[118:121]
	v_mfma_f32_16x16x32_bf16 v[110:113], v[156:159], v[212:215], v[110:113]
	v_mfma_f32_16x16x32_bf16 v[102:105], v[148:151], v[220:223], v[102:105]
	v_mfma_f32_16x16x32_bf16 v[94:97], v[156:159], v[220:223], v[94:97]
	v_mfma_f32_16x16x32_bf16 v[82:85], v[148:151], v[228:231], v[82:85]
	v_mfma_f32_16x16x32_bf16 v[74:77], v[156:159], v[228:231], v[74:77]
	s_setprio 0
	s_setprio 1
	v_mfma_f32_16x16x32_bf16 v[114:117], v[160:163], v[190:193], 0
	v_mfma_f32_16x16x32_bf16 v[106:109], v[168:171], v[190:193], 0
	v_mfma_f32_16x16x32_bf16 v[98:101], v[160:163], v[198:201], 0
	v_mfma_f32_16x16x32_bf16 v[90:93], v[168:171], v[198:201], 0
	v_mfma_f32_16x16x32_bf16 v[86:89], v[160:163], v[216:219], 0
	v_mfma_f32_16x16x32_bf16 v[78:81], v[168:171], v[216:219], 0
	v_mfma_f32_16x16x32_bf16 v[70:73], v[160:163], v[224:227], 0
	v_mfma_f32_16x16x32_bf16 v[66:69], v[168:171], v[224:227], 0
	v_mfma_f32_16x16x32_bf16 v[114:117], v[164:167], v[194:197], v[114:117]
	v_mfma_f32_16x16x32_bf16 v[106:109], v[172:175], v[194:197], v[106:109]
	v_mfma_f32_16x16x32_bf16 v[98:101], v[164:167], v[212:215], v[98:101]
	v_mfma_f32_16x16x32_bf16 v[90:93], v[172:175], v[212:215], v[90:93]
	v_mfma_f32_16x16x32_bf16 v[86:89], v[164:167], v[220:223], v[86:89]
	v_mfma_f32_16x16x32_bf16 v[78:81], v[172:175], v[220:223], v[78:81]
	v_mfma_f32_16x16x32_bf16 v[70:73], v[164:167], v[228:231], v[70:73]
	v_mfma_f32_16x16x32_bf16 v[66:69], v[172:175], v[228:231], v[66:69]
	s_setprio 0
	s_barrier
	s_add_i32 s2, s2, s3
	v_lshl_add_u64 v[140:141], s[48:49], 0, v[0:1]
	s_mov_b32 m0, s2
	ds_read_b128 v[190:193], v143 offset:16384
	ds_read_b128 v[194:197], v143 offset:17408
	ds_read_b128 v[198:201], v143 offset:18432
	ds_read_b128 v[212:215], v143 offset:19456
	ds_read_b128 v[216:219], v143 offset:20480
	ds_read_b128 v[220:223], v143 offset:21504
	ds_read_b128 v[224:227], v143 offset:22528
	ds_read_b128 v[228:231], v143 offset:23552
	global_load_lds_dwordx4 v[140:141], off
	s_add_i32 m0, s2, 0x2000
	s_add_u32 s22, s48, 0xb0000
	v_lshl_add_u64 v[176:177], s[48:49], 0, v[130:131]
	s_addc_u32 s23, s49, 0
	s_add_i32 s2, s8, s3
	global_load_lds_dwordx4 v[176:177], off
	v_lshl_add_u64 v[232:233], s[22:23], 0, v[0:1]
	s_mov_b32 m0, s2
	v_lshl_add_u64 v[234:235], s[50:51], 0, v[132:133]
	global_load_lds_dwordx4 v[232:233], off
	v_lshl_add_u64 v[232:233], s[22:23], 0, v[130:131]
	s_add_i32 m0, s2, 0x2000
	s_nop 0
	global_load_lds_dwordx4 v[232:233], off
	v_lshl_add_u64 v[232:233], s[50:51], 0, v[134:135]
	s_mov_b32 m0, s4
	s_nop 0
	global_load_lds_dwordx4 v[232:233], off
	s_mov_b32 m0, s5
	s_nop 0
	global_load_lds_dwordx4 v[234:235], off
	s_waitcnt vmcnt(8)
	s_waitcnt lgkmcnt(0)
	s_barrier
; #define PG8_STAGE(bufoff, gbase, voff) do { _Pragma("unroll") for (int _i = 0; _i < 2; ++_i) \
;         __builtin_amdgcn_global_load_lds((const unsigned*)((const char*)(gbase) + (voff)[_i]), (PG8_LAS unsigned*)(lds + (bufoff) + ldsw + _i * 8192), 16, 0, 0); } while (0)
; #define PG8_LDA(dst, b, h) do { _Pragma("unroll") for (int m = 0; m < 4; ++m) _Pragma("unroll") for (int k = 0; k < 2; ++k) dst[m][k] = *(const PG8_LAS bf16x8*)(lds + PG8_SA(b, h) + aoff + m * 2048 + k * 1024); } while (0)
; #define PG8_LDB(dst, b, h) do { _Pragma("unroll") for (int n = 0; n < 2; ++n) _Pragma("unroll") for (int k = 0; k < 2; ++k) dst[n][k] = *(const PG8_LAS bf16x8*)(lds + PG8_SB(b, h) + boff + n * 2048 + k * 1024); } while (0)
; #define PG8_MMA(ai, bj, At, Bt) do { __builtin_amdgcn_s_setprio(1); _Pragma("unroll") for (int m = 0; m < 4; ++m) _Pragma("unroll") for (int n = 0; n < 2; ++n) _Pragma("unroll") for (int k = 0; k < 2; ++k) \
;         acc[ai][bj][m][n] = __builtin_amdgcn_mfma_f32_16x16x32_bf16(Bt[n][k], At[m][k], acc[ai][bj][m][n], 0, 0, 0); __builtin_amdgcn_s_setprio(0); } while (0)
; #define PG8_WAIT_V(n) asm volatile("s_waitcnt vmcnt(" #n ")" ::: "memory")
; #define PG8_WAIT_L(n) asm volatile("s_waitcnt lgkmcnt(" #n ")" ::: "memory")
; #define PG8_BAR __builtin_amdgcn_s_barrier()
; #define PG8_SCHED __builtin_amdgcn_sched_barrier(0)
; template <class Epi, class Sched, bool ALIGN_EPI = false, bool SP2 = false>
; __device__ __forceinline__ void gemm_phase(PG8_LAS unsigned char* lds, const Gemm g, const Sched& S, const Epi& E, const int wid_in) {
;     ...
;             PG8_WAIT_V(8); PG8_WAIT_L(0); PG8_BAR; PG8_MMA(1, 0, At, B0); PG8_MMA(1, 1, At, B1); PG8_BAR; PG8_SCHED;
;             PG8_LDB(B0, 1, 0); PG8_LDB(B1, 1, 1); PG8_SCHED; PG8_LDA(At, 1, 0); PG8_STAGE(PG8_SA(0, 1), a2 + hstep, voffA);
;             PG8_WAIT_V(8); PG8_WAIT_L(0); PG8_BAR; PG8_MMA(0, 0, At, B0); PG8_MMA(0, 1, At, B1); PG8_BAR; PG8_SCHED;
	s_setprio 1
	s_waitcnt lgkmcnt(0)
	v_mfma_f32_16x16x32_bf16 v[62:65], v[144:147], v[190:193], 0
	v_mfma_f32_16x16x32_bf16 v[58:61], v[152:155], v[190:193], 0
	v_mfma_f32_16x16x32_bf16 v[54:57], v[144:147], v[198:201], 0
	v_mfma_f32_16x16x32_bf16 v[46:49], v[152:155], v[198:201], 0
	v_mfma_f32_16x16x32_bf16 v[38:41], v[144:147], v[216:219], 0
	v_mfma_f32_16x16x32_bf16 v[30:33], v[152:155], v[216:219], 0
	v_mfma_f32_16x16x32_bf16 v[22:25], v[144:147], v[224:227], 0
	v_mfma_f32_16x16x32_bf16 v[14:17], v[152:155], v[224:227], 0
	v_mfma_f32_16x16x32_bf16 v[62:65], v[148:151], v[194:197], v[62:65]
	v_mfma_f32_16x16x32_bf16 v[58:61], v[156:159], v[194:197], v[58:61]
	v_mfma_f32_16x16x32_bf16 v[54:57], v[148:151], v[212:215], v[54:57]
	v_mfma_f32_16x16x32_bf16 v[46:49], v[156:159], v[212:215], v[46:49]
	v_mfma_f32_16x16x32_bf16 v[38:41], v[148:151], v[220:223], v[38:41]
	v_mfma_f32_16x16x32_bf16 v[30:33], v[156:159], v[220:223], v[30:33]
	v_mfma_f32_16x16x32_bf16 v[22:25], v[148:151], v[228:231], v[22:25]
	v_mfma_f32_16x16x32_bf16 v[14:17], v[156:159], v[228:231], v[14:17]
	s_setprio 0
	s_setprio 1
	v_mfma_f32_16x16x32_bf16 v[50:53], v[160:163], v[190:193], 0
	v_mfma_f32_16x16x32_bf16 v[42:45], v[168:171], v[190:193], 0
	v_mfma_f32_16x16x32_bf16 v[34:37], v[160:163], v[198:201], 0
	v_mfma_f32_16x16x32_bf16 v[26:29], v[168:171], v[198:201], 0
	v_mfma_f32_16x16x32_bf16 v[18:21], v[160:163], v[216:219], 0
	v_mfma_f32_16x16x32_bf16 v[10:13], v[168:171], v[216:219], 0
	v_mfma_f32_16x16x32_bf16 v[6:9], v[160:163], v[224:227], 0
	v_mfma_f32_16x16x32_bf16 v[2:5], v[168:171], v[224:227], 0
	v_mfma_f32_16x16x32_bf16 v[50:53], v[164:167], v[194:197], v[50:53]
	v_mfma_f32_16x16x32_bf16 v[42:45], v[172:175], v[194:197], v[42:45]
	v_mfma_f32_16x16x32_bf16 v[34:37], v[164:167], v[212:215], v[34:37]
	v_mfma_f32_16x16x32_bf16 v[26:29], v[172:175], v[212:215], v[26:29]
	v_mfma_f32_16x16x32_bf16 v[18:21], v[164:167], v[220:223], v[18:21]
	v_mfma_f32_16x16x32_bf16 v[10:13], v[172:175], v[220:223], v[10:13]
	v_mfma_f32_16x16x32_bf16 v[6:9], v[164:167], v[228:231], v[6:9]
	v_mfma_f32_16x16x32_bf16 v[2:5], v[172:175], v[228:231], v[2:5]
	s_setprio 0
	s_barrier
	s_add_i32 s2, 0, 0x18000
	s_add_i32 s8, 0, 0x1c000
	v_add_u32_e32 v156, s2, v142
	v_add_u32_e32 v172, s8, v142
	ds_read_b128 v[144:147], v156
	ds_read_b128 v[148:151], v156 offset:1024
	ds_read_b128 v[152:155], v156 offset:2048
	ds_read_b128 v[156:159], v156 offset:3072
	ds_read_b128 v[160:163], v172
	ds_read_b128 v[164:167], v172 offset:1024
	ds_read_b128 v[168:171], v172 offset:2048
	ds_read_b128 v[172:175], v172 offset:3072
	s_add_u32 s22, s50, 0xb0000
	s_addc_u32 s23, s51, 0
	s_mov_b32 m0, s12
	v_lshl_add_u64 v[236:237], s[22:23], 0, v[134:135]
	ds_read_b128 v[190:193], v143 offset:32768
	ds_read_b128 v[194:197], v143 offset:33792
	ds_read_b128 v[198:201], v143 offset:34816
	ds_read_b128 v[212:215], v143 offset:35840
	ds_read_b128 v[216:219], v143 offset:36864
	ds_read_b128 v[220:223], v143 offset:37888
	ds_read_b128 v[224:227], v143 offset:38912
	ds_read_b128 v[228:231], v143 offset:39936
	global_load_lds_dwordx4 v[236:237], off
	v_lshl_add_u64 v[236:237], s[22:23], 0, v[132:133]
	s_mov_b32 m0, s13
	s_nop 0
	global_load_lds_dwordx4 v[236:237], off
	s_waitcnt vmcnt(8)
	s_waitcnt lgkmcnt(0)
	s_barrier
	s_setprio 1
	s_waitcnt lgkmcnt(0)
	v_mfma_f32_16x16x32_bf16 v[126:129], v[144:147], v[190:193], v[126:129]
	v_mfma_f32_16x16x32_bf16 v[122:125], v[152:155], v[190:193], v[122:125]
	v_mfma_f32_16x16x32_bf16 v[118:121], v[144:147], v[198:201], v[118:121]
	v_mfma_f32_16x16x32_bf16 v[110:113], v[152:155], v[198:201], v[110:113]
	v_mfma_f32_16x16x32_bf16 v[102:105], v[144:147], v[216:219], v[102:105]
	v_mfma_f32_16x16x32_bf16 v[94:97], v[152:155], v[216:219], v[94:97]
	v_mfma_f32_16x16x32_bf16 v[82:85], v[144:147], v[224:227], v[82:85]
	v_mfma_f32_16x16x32_bf16 v[74:77], v[152:155], v[224:227], v[74:77]
	v_mfma_f32_16x16x32_bf16 v[126:129], v[148:151], v[194:197], v[126:129]
	v_mfma_f32_16x16x32_bf16 v[122:125], v[156:159], v[194:197], v[122:125]
	v_mfma_f32_16x16x32_bf16 v[118:121], v[148:151], v[212:215], v[118:121]
	v_mfma_f32_16x16x32_bf16 v[110:113], v[156:159], v[212:215], v[110:113]
	v_mfma_f32_16x16x32_bf16 v[102:105], v[148:151], v[220:223], v[102:105]
	v_mfma_f32_16x16x32_bf16 v[94:97], v[156:159], v[220:223], v[94:97]
	v_mfma_f32_16x16x32_bf16 v[82:85], v[148:151], v[228:231], v[82:85]
	v_mfma_f32_16x16x32_bf16 v[74:77], v[156:159], v[228:231], v[74:77]
	s_setprio 0
	s_setprio 1
	v_mfma_f32_16x16x32_bf16 v[114:117], v[160:163], v[190:193], v[114:117]
	v_mfma_f32_16x16x32_bf16 v[106:109], v[168:171], v[190:193], v[106:109]
	v_mfma_f32_16x16x32_bf16 v[98:101], v[160:163], v[198:201], v[98:101]
	v_mfma_f32_16x16x32_bf16 v[90:93], v[168:171], v[198:201], v[90:93]
	v_mfma_f32_16x16x32_bf16 v[86:89], v[160:163], v[216:219], v[86:89]
	v_mfma_f32_16x16x32_bf16 v[78:81], v[168:171], v[216:219], v[78:81]
	v_mfma_f32_16x16x32_bf16 v[70:73], v[160:163], v[224:227], v[70:73]
	v_mfma_f32_16x16x32_bf16 v[66:69], v[168:171], v[224:227], v[66:69]
	v_mfma_f32_16x16x32_bf16 v[114:117], v[164:167], v[194:197], v[114:117]
	v_mfma_f32_16x16x32_bf16 v[106:109], v[172:175], v[194:197], v[106:109]
	v_mfma_f32_16x16x32_bf16 v[98:101], v[164:167], v[212:215], v[98:101]
	v_mfma_f32_16x16x32_bf16 v[90:93], v[172:175], v[212:215], v[90:93]
	v_mfma_f32_16x16x32_bf16 v[86:89], v[164:167], v[220:223], v[86:89]
	v_mfma_f32_16x16x32_bf16 v[78:81], v[172:175], v[220:223], v[78:81]
	v_mfma_f32_16x16x32_bf16 v[70:73], v[164:167], v[228:231], v[70:73]
	v_mfma_f32_16x16x32_bf16 v[66:69], v[172:175], v[228:231], v[66:69]
	s_setprio 0
	s_barrier
; #define PG8_STAGE(bufoff, gbase, voff) do { _Pragma("unroll") for (int _i = 0; _i < 2; ++_i) \
;         __builtin_amdgcn_global_load_lds((const unsigned*)((const char*)(gbase) + (voff)[_i]), (PG8_LAS unsigned*)(lds + (bufoff) + ldsw + _i * 8192), 16, 0, 0); } while (0)
; #define PG8_LDA(dst, b, h) do { _Pragma("unroll") for (int m = 0; m < 4; ++m) _Pragma("unroll") for (int k = 0; k < 2; ++k) dst[m][k] = *(const PG8_LAS bf16x8*)(lds + PG8_SA(b, h) + aoff + m * 2048 + k * 1024); } while (0)
; #define PG8_MMA(ai, bj, At, Bt) do { __builtin_amdgcn_s_setprio(1); _Pragma("unroll") for (int m = 0; m < 4; ++m) _Pragma("unroll") for (int n = 0; n < 2; ++n) _Pragma("unroll") for (int k = 0; k < 2; ++k) \
;         acc[ai][bj][m][n] = __builtin_amdgcn_mfma_f32_16x16x32_bf16(Bt[n][k], At[m][k], acc[ai][bj][m][n], 0, 0, 0); __builtin_amdgcn_s_setprio(0); } while (0)
; #define PG8_WAIT_V(n) asm volatile("s_waitcnt vmcnt(" #n ")" ::: "memory")
; #define PG8_WAIT_L(n) asm volatile("s_waitcnt lgkmcnt(" #n ")" ::: "memory")
; #define PG8_BAR __builtin_amdgcn_s_barrier()
; #define PG8_SCHED __builtin_amdgcn_sched_barrier(0)
; template <class Epi, class Sched, bool ALIGN_EPI = false, bool SP2 = false>
; __device__ __forceinline__ void gemm_phase(PG8_LAS unsigned char* lds, const Gemm g, const Sched& S, const Epi& E, const int wid_in) {
;     ...
;         for (int t = 0; t < nt; t += 2) {
;     ...
;             PG8_LDA(At, 1, 1); PG8_STAGE(PG8_SB(1, 0), b3, voffB); PG8_STAGE(PG8_SB(1, 1), b3 + hstep, voffB); PG8_STAGE(PG8_SA(1, 0), a3, voffA);
;             PG8_WAIT_V(8); PG8_WAIT_L(0); PG8_BAR; PG8_MMA(1, 0, At, B0); PG8_MMA(1, 1, At, B1); PG8_BAR; PG8_SCHED;
	s_add_i32 s2, s2, s3
	v_lshl_add_u64 v[140:141], v[140:141], 0, s[64:65]
	s_mov_b32 m0, s2
	ds_read_b128 v[190:193], v143 offset:49152
	ds_read_b128 v[194:197], v143 offset:50176
	ds_read_b128 v[198:201], v143 offset:51200
	ds_read_b128 v[212:215], v143 offset:52224
	ds_read_b128 v[216:219], v143 offset:53248
	ds_read_b128 v[220:223], v143 offset:54272
	ds_read_b128 v[224:227], v143 offset:55296
	ds_read_b128 v[228:231], v143 offset:56320
	global_load_lds_dwordx4 v[140:141], off
	s_add_i32 m0, s2, 0x2000
	s_add_u32 s22, s48, 0xb0080
	v_lshl_add_u64 v[140:141], v[176:177], 0, s[64:65]
	s_addc_u32 s23, s49, 0
	s_add_i32 s2, s8, s3
	global_load_lds_dwordx4 v[140:141], off
	v_lshl_add_u64 v[140:141], s[22:23], 0, v[0:1]
	s_mov_b32 m0, s2
	s_nop 0
	global_load_lds_dwordx4 v[140:141], off
	v_lshl_add_u64 v[140:141], s[22:23], 0, v[130:131]
	s_add_i32 m0, s2, 0x2000
	s_nop 0
	global_load_lds_dwordx4 v[140:141], off
	v_lshl_add_u64 v[140:141], v[232:233], 0, s[64:65]
	s_mov_b32 m0, s36
	s_nop 0
	global_load_lds_dwordx4 v[140:141], off
	v_lshl_add_u64 v[140:141], v[234:235], 0, s[64:65]
	s_mov_b32 m0, s37
	s_nop 0
	global_load_lds_dwordx4 v[140:141], off
	s_waitcnt vmcnt(8)
	s_waitcnt lgkmcnt(0)
	s_barrier
	s_setprio 1
	s_waitcnt lgkmcnt(0)
	v_mfma_f32_16x16x32_bf16 v[62:65], v[144:147], v[190:193], v[62:65]
	v_mfma_f32_16x16x32_bf16 v[58:61], v[152:155], v[190:193], v[58:61]
	v_mfma_f32_16x16x32_bf16 v[54:57], v[144:147], v[198:201], v[54:57]
	v_mfma_f32_16x16x32_bf16 v[46:49], v[152:155], v[198:201], v[46:49]
	v_mfma_f32_16x16x32_bf16 v[38:41], v[144:147], v[216:219], v[38:41]
	v_mfma_f32_16x16x32_bf16 v[30:33], v[152:155], v[216:219], v[30:33]
	v_mfma_f32_16x16x32_bf16 v[22:25], v[144:147], v[224:227], v[22:25]
	v_mfma_f32_16x16x32_bf16 v[14:17], v[152:155], v[224:227], v[14:17]
	v_mfma_f32_16x16x32_bf16 v[62:65], v[148:151], v[194:197], v[62:65]
	v_mfma_f32_16x16x32_bf16 v[58:61], v[156:159], v[194:197], v[58:61]
	v_mfma_f32_16x16x32_bf16 v[54:57], v[148:151], v[212:215], v[54:57]
	v_mfma_f32_16x16x32_bf16 v[46:49], v[156:159], v[212:215], v[46:49]
	v_mfma_f32_16x16x32_bf16 v[38:41], v[148:151], v[220:223], v[38:41]
	v_mfma_f32_16x16x32_bf16 v[30:33], v[156:159], v[220:223], v[30:33]
	v_mfma_f32_16x16x32_bf16 v[22:25], v[148:151], v[228:231], v[22:25]
	v_mfma_f32_16x16x32_bf16 v[14:17], v[156:159], v[228:231], v[14:17]
	s_setprio 0
	s_setprio 1
	v_mfma_f32_16x16x32_bf16 v[50:53], v[160:163], v[190:193], v[50:53]
	v_mfma_f32_16x16x32_bf16 v[42:45], v[168:171], v[190:193], v[42:45]
	v_mfma_f32_16x16x32_bf16 v[34:37], v[160:163], v[198:201], v[34:37]
	v_mfma_f32_16x16x32_bf16 v[26:29], v[168:171], v[198:201], v[26:29]
	v_mfma_f32_16x16x32_bf16 v[18:21], v[160:163], v[216:219], v[18:21]
	v_mfma_f32_16x16x32_bf16 v[10:13], v[168:171], v[216:219], v[10:13]
	v_mfma_f32_16x16x32_bf16 v[6:9], v[160:163], v[224:227], v[6:9]
	v_mfma_f32_16x16x32_bf16 v[2:5], v[168:171], v[224:227], v[2:5]
	v_mfma_f32_16x16x32_bf16 v[50:53], v[164:167], v[194:197], v[50:53]
	v_mfma_f32_16x16x32_bf16 v[42:45], v[172:175], v[194:197], v[42:45]
	v_mfma_f32_16x16x32_bf16 v[34:37], v[164:167], v[212:215], v[34:37]
	v_mfma_f32_16x16x32_bf16 v[26:29], v[172:175], v[212:215], v[26:29]
	v_mfma_f32_16x16x32_bf16 v[18:21], v[164:167], v[220:223], v[18:21]
	v_mfma_f32_16x16x32_bf16 v[10:13], v[172:175], v[220:223], v[10:13]
	v_mfma_f32_16x16x32_bf16 v[6:9], v[164:167], v[228:231], v[6:9]
	v_mfma_f32_16x16x32_bf16 v[2:5], v[172:175], v[228:231], v[2:5]
	s_setprio 0
	s_barrier
	s_add_i32 s58, s58, 2
	s_add_u32 s16, s16, 0x100
	s_addc_u32 s57, s57, 0
	s_cmp_gt_u32 s58, 41
	s_mov_b64 s[44:45], s[46:47]

; __global__ void __launch_bounds__(512, 2) hybrid_fwd(Params P) {
	.amdhsa_kernel _Z10hybrid_fwd6Params
		.amdhsa_group_segment_fixed_size 0
		.amdhsa_private_segment_fixed_size 0
		.amdhsa_kernarg_size 456
		.amdhsa_user_sgpr_count 2
		.amdhsa_user_sgpr_dispatch_ptr 0
		.amdhsa_user_sgpr_queue_ptr 0
		.amdhsa_user_sgpr_kernarg_segment_ptr 1
		.amdhsa_user_sgpr_dispatch_id 0
		.amdhsa_user_sgpr_kernarg_preload_length 0
		.amdhsa_user_sgpr_kernarg_preload_offset 0
		.amdhsa_user_sgpr_private_segment_size 0
		.amdhsa_uses_dynamic_stack 0
		.amdhsa_enable_private_segment 0
		.amdhsa_system_sgpr_workgroup_id_x 1
		.amdhsa_system_sgpr_workgroup_id_y 0
		.amdhsa_system_sgpr_workgroup_id_z 0
		.amdhsa_system_sgpr_workgroup_info 0
		.amdhsa_system_vgpr_workitem_id 2
		.amdhsa_next_free_vgpr 248
		.amdhsa_next_free_sgpr 100
		.amdhsa_accum_offset 248
		.amdhsa_reserve_vcc 1
		.amdhsa_float_round_mode_32 0
		.amdhsa_float_round_mode_16_64 0
		.amdhsa_float_denorm_mode_32 3
		.amdhsa_float_denorm_mode_16_64 3
		.amdhsa_dx10_clamp 1
		.amdhsa_ieee_mode 1
		.amdhsa_fp16_overflow 0
		.amdhsa_tg_split 0
		.amdhsa_exception_fp_ieee_invalid_op 0
		.amdhsa_exception_fp_denorm_src 0
		.amdhsa_exception_fp_ieee_div_zero 0
		.amdhsa_exception_fp_ieee_overflow 0
		.amdhsa_exception_fp_ieee_underflow 0
		.amdhsa_exception_fp_ieee_inexact 0
		.amdhsa_exception_int_div_zero 0
	.end_amdhsa_kernel

; __global__ void __launch_bounds__(512, 2) hybrid_fwd(Params P) {
amdhsa.kernels:
  - .agpr_count:     0
    .args:
      - .offset:         0
        .size:           200
        .value_kind:     by_value
      - .offset:         200
        .size:           4
        .value_kind:     hidden_block_count_x
      - .offset:         204
        .size:           4
        .value_kind:     hidden_block_count_y
      - .offset:         208
        .size:           4
        .value_kind:     hidden_block_count_z
      - .offset:         212
        .size:           2
        .value_kind:     hidden_group_size_x
      - .offset:         214
        .size:           2
        .value_kind:     hidden_group_size_y
      - .offset:         216
        .size:           2
        .value_kind:     hidden_group_size_z
      - .offset:         218
        .size:           2
        .value_kind:     hidden_remainder_x
      - .offset:         220
        .size:           2
        .value_kind:     hidden_remainder_y
      - .offset:         222
        .size:           2
        .value_kind:     hidden_remainder_z
      - .offset:         240
        .size:           8
        .value_kind:     hidden_global_offset_x
      - .offset:         248
        .size:           8
        .value_kind:     hidden_global_offset_y
      - .offset:         256
        .size:           8
        .value_kind:     hidden_global_offset_z
      - .offset:         264
        .size:           2
        .value_kind:     hidden_grid_dims
      - .offset:         288
        .size:           8
        .value_kind:     hidden_multigrid_sync_arg
      - .offset:         320
        .size:           4
        .value_kind:     hidden_dynamic_lds_size
    .group_segment_fixed_size: 0
    .kernarg_segment_align: 8
    .kernarg_segment_size: 456
    .language:       OpenCL C
    .language_version:
      - 2
      - 0
    .max_flat_workgroup_size: 512
    .name:           _Z10hybrid_fwd6Params
    .private_segment_fixed_size: 0
    .sgpr_count:     106
    .sgpr_spill_count: 332
    .symbol:         _Z10hybrid_fwd6Params.kd
    .uniform_work_group_size: 1
    .uses_dynamic_stack: false
    .vgpr_count:     248
    .vgpr_spill_count: 0
    .wavefront_size: 64
